# K-loop iteration 0 peeled for every tile: first MFMA of each accumulator takes C=0, the 128 v_mov zeroing per tile removed (all three GEMM variants)
# speedup vs baseline: 1.0215x; 1.0086x over previous
.LBB0_183:
	s_ashr_i32 s9, s8, 31
	s_lshl_b64 s[14:15], s[8:9], 19
	s_add_u32 s14, s34, s14
	s_addc_u32 s15, s35, s15
	s_and_b64 s[16:17], s[12:13], exec
	s_cselect_b32 s9, s15, s21
	s_cselect_b32 s19, s14, s20
	s_ashr_i32 s11, s10, 31
	s_lshl_b64 s[16:17], s[10:11], 19
	s_add_u32 s16, s22, s16
	s_addc_u32 s17, s36, s17
	s_and_b64 s[26:27], s[12:13], exec
	s_cselect_b32 s11, s17, s25
	s_cselect_b32 s46, s16, s24
	s_add_u32 s20, s20, 0x40080
	s_addc_u32 s21, s21, 0
	s_add_u32 s47, s24, 0x100
	s_addc_u32 s48, s25, 0
	s_mov_b32 s49, -2
	s_waitcnt vmcnt(0)
	s_branch .Lit0_prj
.LBB0_184:
	s_add_u32 s24, s20, 0xfffc0080
	s_addc_u32 s25, s21, -1
	s_add_i32 s50, 0, 0x10000
	s_cmp_eq_u32 s49, 12
	s_cselect_b32 s27, s9, s25
	s_cselect_b32 s26, s19, s24
	s_cselect_b32 s25, s11, s48
	s_cselect_b32 s24, s46, s47
	s_add_i32 s77, 0, 0x14000
	v_add_u32_e32 v174, s50, v145
	v_add_u32_e32 v190, s77, v145
	ds_read_b128 v[150:153], v174
	ds_read_b128 v[154:157], v174 offset:1024
	ds_read_b128 v[170:173], v174 offset:2048
	ds_read_b128 v[174:177], v174 offset:3072
	ds_read_b128 v[178:181], v190
	ds_read_b128 v[182:185], v190 offset:1024
	ds_read_b128 v[186:189], v190 offset:2048
	ds_read_b128 v[190:193], v190 offset:3072
	v_lshl_add_u64 v[226:227], s[20:21], 0, v[140:141]
	s_add_i32 m0, s38, 0xc000
	ds_read_b128 v[194:197], v149
	ds_read_b128 v[198:201], v149 offset:1024
	ds_read_b128 v[202:205], v149 offset:2048
	ds_read_b128 v[206:209], v149 offset:3072
	ds_read_b128 v[210:213], v149 offset:4096
	ds_read_b128 v[214:217], v149 offset:5120
	ds_read_b128 v[218:221], v149 offset:6144
	ds_read_b128 v[222:225], v149 offset:7168
	global_load_lds_dwordx4 v[226:227], off
	v_lshl_add_u64 v[226:227], s[20:21], 0, v[142:143]
	s_add_i32 m0, s38, 0xe000
	s_nop 0
	global_load_lds_dwordx4 v[226:227], off
	s_waitcnt vmcnt(8)
	s_waitcnt lgkmcnt(0)
	s_barrier
	s_setprio 3
	s_waitcnt lgkmcnt(0)
	v_mfma_f32_16x16x32_bf16 v[124:127], v[150:153], v[194:197], v[124:127]
	v_mfma_f32_16x16x32_bf16 v[120:123], v[170:173], v[194:197], v[120:123]
	v_mfma_f32_16x16x32_bf16 v[112:115], v[150:153], v[202:205], v[112:115]
	v_mfma_f32_16x16x32_bf16 v[104:107], v[170:173], v[202:205], v[104:107]
	v_mfma_f32_16x16x32_bf16 v[96:99], v[150:153], v[210:213], v[96:99]
	v_mfma_f32_16x16x32_bf16 v[88:91], v[170:173], v[210:213], v[88:91]
	v_mfma_f32_16x16x32_bf16 v[80:83], v[150:153], v[218:221], v[80:83]
	v_mfma_f32_16x16x32_bf16 v[72:75], v[170:173], v[218:221], v[72:75]
	v_mfma_f32_16x16x32_bf16 v[124:127], v[154:157], v[198:201], v[124:127]
	v_mfma_f32_16x16x32_bf16 v[120:123], v[174:177], v[198:201], v[120:123]
	v_mfma_f32_16x16x32_bf16 v[112:115], v[154:157], v[206:209], v[112:115]
	v_mfma_f32_16x16x32_bf16 v[104:107], v[174:177], v[206:209], v[104:107]
	v_mfma_f32_16x16x32_bf16 v[96:99], v[154:157], v[214:217], v[96:99]
	v_mfma_f32_16x16x32_bf16 v[88:91], v[174:177], v[214:217], v[88:91]
	v_mfma_f32_16x16x32_bf16 v[80:83], v[154:157], v[222:225], v[80:83]
	v_mfma_f32_16x16x32_bf16 v[72:75], v[174:177], v[222:225], v[72:75]
	s_setprio 0
	s_setprio 3
	v_mfma_f32_16x16x32_bf16 v[116:119], v[178:181], v[194:197], v[116:119]
	v_mfma_f32_16x16x32_bf16 v[108:111], v[186:189], v[194:197], v[108:111]
	v_mfma_f32_16x16x32_bf16 v[100:103], v[178:181], v[202:205], v[100:103]
	v_mfma_f32_16x16x32_bf16 v[92:95], v[186:189], v[202:205], v[92:95]
	v_mfma_f32_16x16x32_bf16 v[84:87], v[178:181], v[210:213], v[84:87]
	v_mfma_f32_16x16x32_bf16 v[76:79], v[186:189], v[210:213], v[76:79]
	v_mfma_f32_16x16x32_bf16 v[68:71], v[178:181], v[218:221], v[68:71]
	v_mfma_f32_16x16x32_bf16 v[64:67], v[186:189], v[218:221], v[64:67]
	v_mfma_f32_16x16x32_bf16 v[116:119], v[182:185], v[198:201], v[116:119]
	v_mfma_f32_16x16x32_bf16 v[108:111], v[190:193], v[198:201], v[108:111]
	v_mfma_f32_16x16x32_bf16 v[100:103], v[182:185], v[206:209], v[100:103]
	v_mfma_f32_16x16x32_bf16 v[92:95], v[190:193], v[206:209], v[92:95]
	v_mfma_f32_16x16x32_bf16 v[84:87], v[182:185], v[214:217], v[84:87]
	v_mfma_f32_16x16x32_bf16 v[76:79], v[190:193], v[214:217], v[76:79]
	v_mfma_f32_16x16x32_bf16 v[68:71], v[182:185], v[222:225], v[68:71]
	v_mfma_f32_16x16x32_bf16 v[64:67], v[190:193], v[222:225], v[64:67]
	s_setprio 0
	s_barrier
	s_add_i32 s50, s50, s37
	v_lshl_add_u64 v[226:227], s[24:25], 0, v[128:129]
	s_mov_b32 m0, s50
	ds_read_b128 v[194:197], v149 offset:16384
	ds_read_b128 v[198:201], v149 offset:17408
	ds_read_b128 v[202:205], v149 offset:18432
	ds_read_b128 v[206:209], v149 offset:19456
	ds_read_b128 v[210:213], v149 offset:20480
	ds_read_b128 v[214:217], v149 offset:21504
	ds_read_b128 v[218:221], v149 offset:22528
	ds_read_b128 v[222:225], v149 offset:23552
	global_load_lds_dwordx4 v[226:227], off
	s_add_i32 m0, s50, 0x2000
	s_add_u32 s50, s24, 0x40000
	v_lshl_add_u64 v[228:229], s[24:25], 0, v[134:135]
	s_addc_u32 s51, s25, 0
	s_add_i32 s77, s77, s37
	global_load_lds_dwordx4 v[228:229], off
	v_lshl_add_u64 v[230:231], s[50:51], 0, v[128:129]
	s_mov_b32 m0, s77
	v_lshl_add_u64 v[232:233], s[26:27], 0, v[136:137]
	global_load_lds_dwordx4 v[230:231], off
	v_lshl_add_u64 v[230:231], s[50:51], 0, v[134:135]
	s_add_i32 m0, s77, 0x2000
	s_nop 0
	global_load_lds_dwordx4 v[230:231], off
	v_lshl_add_u64 v[230:231], s[26:27], 0, v[138:139]
	s_mov_b32 m0, s38
	s_nop 0
	global_load_lds_dwordx4 v[230:231], off
	s_mov_b32 m0, s39
	s_nop 0
	global_load_lds_dwordx4 v[232:233], off
	s_waitcnt vmcnt(8)
	s_waitcnt lgkmcnt(0)
	s_barrier
	s_setprio 3
	s_waitcnt lgkmcnt(0)
	v_mfma_f32_16x16x32_bf16 v[60:63], v[150:153], v[194:197], v[60:63]
	v_mfma_f32_16x16x32_bf16 v[56:59], v[170:173], v[194:197], v[56:59]
	v_mfma_f32_16x16x32_bf16 v[48:51], v[150:153], v[202:205], v[48:51]
	v_mfma_f32_16x16x32_bf16 v[40:43], v[170:173], v[202:205], v[40:43]
	v_mfma_f32_16x16x32_bf16 v[32:35], v[150:153], v[210:213], v[32:35]
	v_mfma_f32_16x16x32_bf16 v[24:27], v[170:173], v[210:213], v[24:27]
	v_mfma_f32_16x16x32_bf16 v[16:19], v[150:153], v[218:221], v[16:19]
	v_mfma_f32_16x16x32_bf16 v[8:11], v[170:173], v[218:221], v[8:11]
	v_mfma_f32_16x16x32_bf16 v[60:63], v[154:157], v[198:201], v[60:63]
	v_mfma_f32_16x16x32_bf16 v[56:59], v[174:177], v[198:201], v[56:59]
	v_mfma_f32_16x16x32_bf16 v[48:51], v[154:157], v[206:209], v[48:51]
	v_mfma_f32_16x16x32_bf16 v[40:43], v[174:177], v[206:209], v[40:43]
	v_mfma_f32_16x16x32_bf16 v[32:35], v[154:157], v[214:217], v[32:35]
	v_mfma_f32_16x16x32_bf16 v[24:27], v[174:177], v[214:217], v[24:27]
	v_mfma_f32_16x16x32_bf16 v[16:19], v[154:157], v[222:225], v[16:19]
	v_mfma_f32_16x16x32_bf16 v[8:11], v[174:177], v[222:225], v[8:11]
	s_setprio 0
	s_setprio 3
	v_mfma_f32_16x16x32_bf16 v[52:55], v[178:181], v[194:197], v[52:55]
	v_mfma_f32_16x16x32_bf16 v[44:47], v[186:189], v[194:197], v[44:47]
	v_mfma_f32_16x16x32_bf16 v[36:39], v[178:181], v[202:205], v[36:39]
	v_mfma_f32_16x16x32_bf16 v[28:31], v[186:189], v[202:205], v[28:31]
	v_mfma_f32_16x16x32_bf16 v[20:23], v[178:181], v[210:213], v[20:23]
	v_mfma_f32_16x16x32_bf16 v[12:15], v[186:189], v[210:213], v[12:15]
	v_mfma_f32_16x16x32_bf16 v[4:7], v[178:181], v[218:221], v[4:7]
	v_mfma_f32_16x16x32_bf16 v[0:3], v[186:189], v[218:221], v[0:3]
	v_mfma_f32_16x16x32_bf16 v[52:55], v[182:185], v[198:201], v[52:55]
	v_mfma_f32_16x16x32_bf16 v[44:47], v[190:193], v[198:201], v[44:47]
	v_mfma_f32_16x16x32_bf16 v[36:39], v[182:185], v[206:209], v[36:39]
	v_mfma_f32_16x16x32_bf16 v[28:31], v[190:193], v[206:209], v[28:31]
	v_mfma_f32_16x16x32_bf16 v[20:23], v[182:185], v[214:217], v[20:23]
	v_mfma_f32_16x16x32_bf16 v[12:15], v[190:193], v[214:217], v[12:15]
	v_mfma_f32_16x16x32_bf16 v[4:7], v[182:185], v[222:225], v[4:7]
	v_mfma_f32_16x16x32_bf16 v[0:3], v[190:193], v[222:225], v[0:3]
	s_setprio 0
	s_barrier
	s_add_i32 s50, 0, 0x18000
	s_add_i32 s51, 0, 0x1c000
	v_add_u32_e32 v174, s50, v145
	v_add_u32_e32 v190, s51, v145
	ds_read_b128 v[150:153], v174
	ds_read_b128 v[154:157], v174 offset:1024
	ds_read_b128 v[170:173], v174 offset:2048
	ds_read_b128 v[174:177], v174 offset:3072
	ds_read_b128 v[178:181], v190
	ds_read_b128 v[182:185], v190 offset:1024
	ds_read_b128 v[186:189], v190 offset:2048
	ds_read_b128 v[190:193], v190 offset:3072
	s_add_u32 s26, s26, 0x40000
	s_addc_u32 s27, s27, 0
	s_mov_b32 m0, s40
	v_lshl_add_u64 v[234:235], s[26:27], 0, v[138:139]
	ds_read_b128 v[194:197], v149 offset:32768
	ds_read_b128 v[198:201], v149 offset:33792
	ds_read_b128 v[202:205], v149 offset:34816
	ds_read_b128 v[206:209], v149 offset:35840
	ds_read_b128 v[210:213], v149 offset:36864
	ds_read_b128 v[214:217], v149 offset:37888
	ds_read_b128 v[218:221], v149 offset:38912
	ds_read_b128 v[222:225], v149 offset:39936
	global_load_lds_dwordx4 v[234:235], off
	v_lshl_add_u64 v[234:235], s[26:27], 0, v[136:137]
	s_mov_b32 m0, s41
	s_nop 0
	global_load_lds_dwordx4 v[234:235], off
	s_waitcnt vmcnt(8)
	s_waitcnt lgkmcnt(0)
	s_barrier
	s_setprio 3
	s_waitcnt lgkmcnt(0)
	v_mfma_f32_16x16x32_bf16 v[124:127], v[150:153], v[194:197], v[124:127]
	v_mfma_f32_16x16x32_bf16 v[120:123], v[170:173], v[194:197], v[120:123]
	v_mfma_f32_16x16x32_bf16 v[112:115], v[150:153], v[202:205], v[112:115]
	v_mfma_f32_16x16x32_bf16 v[104:107], v[170:173], v[202:205], v[104:107]
	v_mfma_f32_16x16x32_bf16 v[96:99], v[150:153], v[210:213], v[96:99]
	v_mfma_f32_16x16x32_bf16 v[88:91], v[170:173], v[210:213], v[88:91]
	v_mfma_f32_16x16x32_bf16 v[80:83], v[150:153], v[218:221], v[80:83]
	v_mfma_f32_16x16x32_bf16 v[72:75], v[170:173], v[218:221], v[72:75]
	v_mfma_f32_16x16x32_bf16 v[124:127], v[154:157], v[198:201], v[124:127]
	v_mfma_f32_16x16x32_bf16 v[120:123], v[174:177], v[198:201], v[120:123]
	v_mfma_f32_16x16x32_bf16 v[112:115], v[154:157], v[206:209], v[112:115]
	v_mfma_f32_16x16x32_bf16 v[104:107], v[174:177], v[206:209], v[104:107]
	v_mfma_f32_16x16x32_bf16 v[96:99], v[154:157], v[214:217], v[96:99]
	v_mfma_f32_16x16x32_bf16 v[88:91], v[174:177], v[214:217], v[88:91]
	v_mfma_f32_16x16x32_bf16 v[80:83], v[154:157], v[222:225], v[80:83]
	v_mfma_f32_16x16x32_bf16 v[72:75], v[174:177], v[222:225], v[72:75]
	s_setprio 0
	s_setprio 3
	v_mfma_f32_16x16x32_bf16 v[116:119], v[178:181], v[194:197], v[116:119]
	v_mfma_f32_16x16x32_bf16 v[108:111], v[186:189], v[194:197], v[108:111]
	v_mfma_f32_16x16x32_bf16 v[100:103], v[178:181], v[202:205], v[100:103]
	v_mfma_f32_16x16x32_bf16 v[92:95], v[186:189], v[202:205], v[92:95]
	v_mfma_f32_16x16x32_bf16 v[84:87], v[178:181], v[210:213], v[84:87]
	v_mfma_f32_16x16x32_bf16 v[76:79], v[186:189], v[210:213], v[76:79]
	v_mfma_f32_16x16x32_bf16 v[68:71], v[178:181], v[218:221], v[68:71]
	v_mfma_f32_16x16x32_bf16 v[64:67], v[186:189], v[218:221], v[64:67]
	v_mfma_f32_16x16x32_bf16 v[116:119], v[182:185], v[198:201], v[116:119]
	v_mfma_f32_16x16x32_bf16 v[108:111], v[190:193], v[198:201], v[108:111]
	v_mfma_f32_16x16x32_bf16 v[100:103], v[182:185], v[206:209], v[100:103]
	v_mfma_f32_16x16x32_bf16 v[92:95], v[190:193], v[206:209], v[92:95]
	v_mfma_f32_16x16x32_bf16 v[84:87], v[182:185], v[214:217], v[84:87]
	v_mfma_f32_16x16x32_bf16 v[76:79], v[190:193], v[214:217], v[76:79]
	v_mfma_f32_16x16x32_bf16 v[68:71], v[182:185], v[222:225], v[68:71]
	v_mfma_f32_16x16x32_bf16 v[64:67], v[190:193], v[222:225], v[64:67]
	s_setprio 0
	s_barrier
	s_add_i32 s26, s50, s37
	v_lshl_add_u64 v[226:227], v[226:227], 0, s[84:85]
	s_mov_b32 m0, s26
	ds_read_b128 v[194:197], v149 offset:49152
	ds_read_b128 v[198:201], v149 offset:50176
	ds_read_b128 v[202:205], v149 offset:51200
	ds_read_b128 v[206:209], v149 offset:52224
	ds_read_b128 v[210:213], v149 offset:53248
	ds_read_b128 v[214:217], v149 offset:54272
	ds_read_b128 v[218:221], v149 offset:55296
	ds_read_b128 v[222:225], v149 offset:56320
	global_load_lds_dwordx4 v[226:227], off
	s_add_i32 m0, s26, 0x2000
	s_add_u32 s24, s24, 0x40080
	v_lshl_add_u64 v[226:227], v[228:229], 0, s[84:85]
	s_addc_u32 s25, s25, 0
	s_add_i32 s26, s51, s37
	global_load_lds_dwordx4 v[226:227], off
	v_lshl_add_u64 v[226:227], s[24:25], 0, v[128:129]
	s_mov_b32 m0, s26
	s_nop 0
	global_load_lds_dwordx4 v[226:227], off
	v_lshl_add_u64 v[226:227], s[24:25], 0, v[134:135]
	s_add_i32 m0, s26, 0x2000
	s_nop 0
	global_load_lds_dwordx4 v[226:227], off
	v_lshl_add_u64 v[226:227], v[230:231], 0, s[84:85]
	s_mov_b32 m0, s42
	s_nop 0
	global_load_lds_dwordx4 v[226:227], off
	v_lshl_add_u64 v[226:227], v[232:233], 0, s[84:85]
	s_mov_b32 m0, s43
	s_nop 0
	global_load_lds_dwordx4 v[226:227], off
	s_waitcnt vmcnt(8)
	s_waitcnt lgkmcnt(0)
	s_barrier
	s_setprio 3
	s_waitcnt lgkmcnt(0)
	v_mfma_f32_16x16x32_bf16 v[60:63], v[150:153], v[194:197], v[60:63]
	v_mfma_f32_16x16x32_bf16 v[56:59], v[170:173], v[194:197], v[56:59]
	v_mfma_f32_16x16x32_bf16 v[48:51], v[150:153], v[202:205], v[48:51]
	v_mfma_f32_16x16x32_bf16 v[40:43], v[170:173], v[202:205], v[40:43]
	v_mfma_f32_16x16x32_bf16 v[32:35], v[150:153], v[210:213], v[32:35]
	v_mfma_f32_16x16x32_bf16 v[24:27], v[170:173], v[210:213], v[24:27]
	v_mfma_f32_16x16x32_bf16 v[16:19], v[150:153], v[218:221], v[16:19]
	v_mfma_f32_16x16x32_bf16 v[8:11], v[170:173], v[218:221], v[8:11]
	v_mfma_f32_16x16x32_bf16 v[60:63], v[154:157], v[198:201], v[60:63]
	v_mfma_f32_16x16x32_bf16 v[56:59], v[174:177], v[198:201], v[56:59]
	v_mfma_f32_16x16x32_bf16 v[48:51], v[154:157], v[206:209], v[48:51]
	v_mfma_f32_16x16x32_bf16 v[40:43], v[174:177], v[206:209], v[40:43]
	v_mfma_f32_16x16x32_bf16 v[32:35], v[154:157], v[214:217], v[32:35]
	v_mfma_f32_16x16x32_bf16 v[24:27], v[174:177], v[214:217], v[24:27]
	v_mfma_f32_16x16x32_bf16 v[16:19], v[154:157], v[222:225], v[16:19]
	v_mfma_f32_16x16x32_bf16 v[8:11], v[174:177], v[222:225], v[8:11]
	s_setprio 0
	s_setprio 3
	v_mfma_f32_16x16x32_bf16 v[52:55], v[178:181], v[194:197], v[52:55]
	v_mfma_f32_16x16x32_bf16 v[44:47], v[186:189], v[194:197], v[44:47]
	v_mfma_f32_16x16x32_bf16 v[36:39], v[178:181], v[202:205], v[36:39]
	v_mfma_f32_16x16x32_bf16 v[28:31], v[186:189], v[202:205], v[28:31]
	v_mfma_f32_16x16x32_bf16 v[20:23], v[178:181], v[210:213], v[20:23]
	v_mfma_f32_16x16x32_bf16 v[12:15], v[186:189], v[210:213], v[12:15]
	v_mfma_f32_16x16x32_bf16 v[4:7], v[178:181], v[218:221], v[4:7]
	v_mfma_f32_16x16x32_bf16 v[0:3], v[186:189], v[218:221], v[0:3]
	v_mfma_f32_16x16x32_bf16 v[52:55], v[182:185], v[198:201], v[52:55]
	v_mfma_f32_16x16x32_bf16 v[44:47], v[190:193], v[198:201], v[44:47]
	v_mfma_f32_16x16x32_bf16 v[36:39], v[182:185], v[206:209], v[36:39]
	v_mfma_f32_16x16x32_bf16 v[28:31], v[190:193], v[206:209], v[28:31]
	v_mfma_f32_16x16x32_bf16 v[20:23], v[182:185], v[214:217], v[20:23]
	v_mfma_f32_16x16x32_bf16 v[12:15], v[190:193], v[214:217], v[12:15]
	v_mfma_f32_16x16x32_bf16 v[4:7], v[182:185], v[222:225], v[4:7]
	v_mfma_f32_16x16x32_bf16 v[0:3], v[190:193], v[222:225], v[0:3]
	s_setprio 0
	s_barrier
	s_add_i32 s49, s49, 2
	s_add_u32 s20, s20, 0x100
	s_addc_u32 s21, s21, 0
	s_add_u32 s47, s47, 0x100
	s_addc_u32 s48, s48, 0
	s_cmp_gt_u32 s49, 13
	s_cbranch_scc0 .LBB0_184
	s_branch .Lit0_prj_skip
.Lit0_prj:
	s_add_u32 s24, s20, 0xfffc0080
	s_addc_u32 s25, s21, -1
	s_add_i32 s50, 0, 0x10000
	s_cmp_eq_u32 s49, 12
	s_cselect_b32 s27, s9, s25
	s_cselect_b32 s26, s19, s24
	s_cselect_b32 s25, s11, s48
	s_cselect_b32 s24, s46, s47
	s_add_i32 s77, 0, 0x14000
	v_add_u32_e32 v174, s50, v145
	v_add_u32_e32 v190, s77, v145
	ds_read_b128 v[150:153], v174
	ds_read_b128 v[154:157], v174 offset:1024
	ds_read_b128 v[170:173], v174 offset:2048
	ds_read_b128 v[174:177], v174 offset:3072
	ds_read_b128 v[178:181], v190
	ds_read_b128 v[182:185], v190 offset:1024
	ds_read_b128 v[186:189], v190 offset:2048
	ds_read_b128 v[190:193], v190 offset:3072
	v_lshl_add_u64 v[226:227], s[20:21], 0, v[140:141]
	s_add_i32 m0, s38, 0xc000
	ds_read_b128 v[194:197], v149
	ds_read_b128 v[198:201], v149 offset:1024
	ds_read_b128 v[202:205], v149 offset:2048
	ds_read_b128 v[206:209], v149 offset:3072
	ds_read_b128 v[210:213], v149 offset:4096
	ds_read_b128 v[214:217], v149 offset:5120
	ds_read_b128 v[218:221], v149 offset:6144
	ds_read_b128 v[222:225], v149 offset:7168
	global_load_lds_dwordx4 v[226:227], off
	v_lshl_add_u64 v[226:227], s[20:21], 0, v[142:143]
	s_add_i32 m0, s38, 0xe000
	s_nop 0
	global_load_lds_dwordx4 v[226:227], off
	s_waitcnt vmcnt(8)
	s_waitcnt lgkmcnt(0)
	s_barrier
	s_setprio 3
	s_waitcnt lgkmcnt(0)
	v_mfma_f32_16x16x32_bf16 v[124:127], v[150:153], v[194:197], 0
	v_mfma_f32_16x16x32_bf16 v[120:123], v[170:173], v[194:197], 0
	v_mfma_f32_16x16x32_bf16 v[112:115], v[150:153], v[202:205], 0
	v_mfma_f32_16x16x32_bf16 v[104:107], v[170:173], v[202:205], 0
	v_mfma_f32_16x16x32_bf16 v[96:99], v[150:153], v[210:213], 0
	v_mfma_f32_16x16x32_bf16 v[88:91], v[170:173], v[210:213], 0
	v_mfma_f32_16x16x32_bf16 v[80:83], v[150:153], v[218:221], 0
	v_mfma_f32_16x16x32_bf16 v[72:75], v[170:173], v[218:221], 0
	v_mfma_f32_16x16x32_bf16 v[124:127], v[154:157], v[198:201], v[124:127]
	v_mfma_f32_16x16x32_bf16 v[120:123], v[174:177], v[198:201], v[120:123]
	v_mfma_f32_16x16x32_bf16 v[112:115], v[154:157], v[206:209], v[112:115]
	v_mfma_f32_16x16x32_bf16 v[104:107], v[174:177], v[206:209], v[104:107]
	v_mfma_f32_16x16x32_bf16 v[96:99], v[154:157], v[214:217], v[96:99]
	v_mfma_f32_16x16x32_bf16 v[88:91], v[174:177], v[214:217], v[88:91]
	v_mfma_f32_16x16x32_bf16 v[80:83], v[154:157], v[222:225], v[80:83]
	v_mfma_f32_16x16x32_bf16 v[72:75], v[174:177], v[222:225], v[72:75]
	s_setprio 0
	s_setprio 3
	v_mfma_f32_16x16x32_bf16 v[116:119], v[178:181], v[194:197], 0
	v_mfma_f32_16x16x32_bf16 v[108:111], v[186:189], v[194:197], 0
	v_mfma_f32_16x16x32_bf16 v[100:103], v[178:181], v[202:205], 0
	v_mfma_f32_16x16x32_bf16 v[92:95], v[186:189], v[202:205], 0
	v_mfma_f32_16x16x32_bf16 v[84:87], v[178:181], v[210:213], 0
	v_mfma_f32_16x16x32_bf16 v[76:79], v[186:189], v[210:213], 0
	v_mfma_f32_16x16x32_bf16 v[68:71], v[178:181], v[218:221], 0
	v_mfma_f32_16x16x32_bf16 v[64:67], v[186:189], v[218:221], 0
	v_mfma_f32_16x16x32_bf16 v[116:119], v[182:185], v[198:201], v[116:119]
	v_mfma_f32_16x16x32_bf16 v[108:111], v[190:193], v[198:201], v[108:111]
	v_mfma_f32_16x16x32_bf16 v[100:103], v[182:185], v[206:209], v[100:103]
	v_mfma_f32_16x16x32_bf16 v[92:95], v[190:193], v[206:209], v[92:95]
	v_mfma_f32_16x16x32_bf16 v[84:87], v[182:185], v[214:217], v[84:87]
	v_mfma_f32_16x16x32_bf16 v[76:79], v[190:193], v[214:217], v[76:79]
	v_mfma_f32_16x16x32_bf16 v[68:71], v[182:185], v[222:225], v[68:71]
	v_mfma_f32_16x16x32_bf16 v[64:67], v[190:193], v[222:225], v[64:67]
	s_setprio 0
	s_barrier
	s_add_i32 s50, s50, s37
	v_lshl_add_u64 v[226:227], s[24:25], 0, v[128:129]
	s_mov_b32 m0, s50
	ds_read_b128 v[194:197], v149 offset:16384
	ds_read_b128 v[198:201], v149 offset:17408
	ds_read_b128 v[202:205], v149 offset:18432
	ds_read_b128 v[206:209], v149 offset:19456
	ds_read_b128 v[210:213], v149 offset:20480
	ds_read_b128 v[214:217], v149 offset:21504
	ds_read_b128 v[218:221], v149 offset:22528
	ds_read_b128 v[222:225], v149 offset:23552
	global_load_lds_dwordx4 v[226:227], off
	s_add_i32 m0, s50, 0x2000
	s_add_u32 s50, s24, 0x40000
	v_lshl_add_u64 v[228:229], s[24:25], 0, v[134:135]
	s_addc_u32 s51, s25, 0
	s_add_i32 s77, s77, s37
	global_load_lds_dwordx4 v[228:229], off
	v_lshl_add_u64 v[230:231], s[50:51], 0, v[128:129]
	s_mov_b32 m0, s77
	v_lshl_add_u64 v[232:233], s[26:27], 0, v[136:137]
	global_load_lds_dwordx4 v[230:231], off
	v_lshl_add_u64 v[230:231], s[50:51], 0, v[134:135]
	s_add_i32 m0, s77, 0x2000
	s_nop 0
	global_load_lds_dwordx4 v[230:231], off
	v_lshl_add_u64 v[230:231], s[26:27], 0, v[138:139]
	s_mov_b32 m0, s38
	s_nop 0
	global_load_lds_dwordx4 v[230:231], off
	s_mov_b32 m0, s39
	s_nop 0
	global_load_lds_dwordx4 v[232:233], off
	s_waitcnt vmcnt(8)
	s_waitcnt lgkmcnt(0)
	s_barrier
	s_setprio 3
	s_waitcnt lgkmcnt(0)
	v_mfma_f32_16x16x32_bf16 v[60:63], v[150:153], v[194:197], 0
	v_mfma_f32_16x16x32_bf16 v[56:59], v[170:173], v[194:197], 0
	v_mfma_f32_16x16x32_bf16 v[48:51], v[150:153], v[202:205], 0
	v_mfma_f32_16x16x32_bf16 v[40:43], v[170:173], v[202:205], 0
	v_mfma_f32_16x16x32_bf16 v[32:35], v[150:153], v[210:213], 0
	v_mfma_f32_16x16x32_bf16 v[24:27], v[170:173], v[210:213], 0
	v_mfma_f32_16x16x32_bf16 v[16:19], v[150:153], v[218:221], 0
	v_mfma_f32_16x16x32_bf16 v[8:11], v[170:173], v[218:221], 0
	v_mfma_f32_16x16x32_bf16 v[60:63], v[154:157], v[198:201], v[60:63]
	v_mfma_f32_16x16x32_bf16 v[56:59], v[174:177], v[198:201], v[56:59]
	v_mfma_f32_16x16x32_bf16 v[48:51], v[154:157], v[206:209], v[48:51]
	v_mfma_f32_16x16x32_bf16 v[40:43], v[174:177], v[206:209], v[40:43]
	v_mfma_f32_16x16x32_bf16 v[32:35], v[154:157], v[214:217], v[32:35]
	v_mfma_f32_16x16x32_bf16 v[24:27], v[174:177], v[214:217], v[24:27]
	v_mfma_f32_16x16x32_bf16 v[16:19], v[154:157], v[222:225], v[16:19]
	v_mfma_f32_16x16x32_bf16 v[8:11], v[174:177], v[222:225], v[8:11]
	s_setprio 0
	s_setprio 3
	v_mfma_f32_16x16x32_bf16 v[52:55], v[178:181], v[194:197], 0
	v_mfma_f32_16x16x32_bf16 v[44:47], v[186:189], v[194:197], 0
	v_mfma_f32_16x16x32_bf16 v[36:39], v[178:181], v[202:205], 0
	v_mfma_f32_16x16x32_bf16 v[28:31], v[186:189], v[202:205], 0
	v_mfma_f32_16x16x32_bf16 v[20:23], v[178:181], v[210:213], 0
	v_mfma_f32_16x16x32_bf16 v[12:15], v[186:189], v[210:213], 0
	v_mfma_f32_16x16x32_bf16 v[4:7], v[178:181], v[218:221], 0
	v_mfma_f32_16x16x32_bf16 v[0:3], v[186:189], v[218:221], 0
	v_mfma_f32_16x16x32_bf16 v[52:55], v[182:185], v[198:201], v[52:55]
	v_mfma_f32_16x16x32_bf16 v[44:47], v[190:193], v[198:201], v[44:47]
	v_mfma_f32_16x16x32_bf16 v[36:39], v[182:185], v[206:209], v[36:39]
	v_mfma_f32_16x16x32_bf16 v[28:31], v[190:193], v[206:209], v[28:31]
	v_mfma_f32_16x16x32_bf16 v[20:23], v[182:185], v[214:217], v[20:23]
	v_mfma_f32_16x16x32_bf16 v[12:15], v[190:193], v[214:217], v[12:15]
	v_mfma_f32_16x16x32_bf16 v[4:7], v[182:185], v[222:225], v[4:7]
	v_mfma_f32_16x16x32_bf16 v[0:3], v[190:193], v[222:225], v[0:3]
	s_setprio 0
	s_barrier
	s_add_i32 s50, 0, 0x18000
	s_add_i32 s51, 0, 0x1c000
	v_add_u32_e32 v174, s50, v145
	v_add_u32_e32 v190, s51, v145
	ds_read_b128 v[150:153], v174
	ds_read_b128 v[154:157], v174 offset:1024
	ds_read_b128 v[170:173], v174 offset:2048
	ds_read_b128 v[174:177], v174 offset:3072
	ds_read_b128 v[178:181], v190
	ds_read_b128 v[182:185], v190 offset:1024
	ds_read_b128 v[186:189], v190 offset:2048
	ds_read_b128 v[190:193], v190 offset:3072
	s_add_u32 s26, s26, 0x40000
	s_addc_u32 s27, s27, 0
	s_mov_b32 m0, s40
	v_lshl_add_u64 v[234:235], s[26:27], 0, v[138:139]
	ds_read_b128 v[194:197], v149 offset:32768
	ds_read_b128 v[198:201], v149 offset:33792
	ds_read_b128 v[202:205], v149 offset:34816
	ds_read_b128 v[206:209], v149 offset:35840
	ds_read_b128 v[210:213], v149 offset:36864
	ds_read_b128 v[214:217], v149 offset:37888
	ds_read_b128 v[218:221], v149 offset:38912
	ds_read_b128 v[222:225], v149 offset:39936
	global_load_lds_dwordx4 v[234:235], off
	v_lshl_add_u64 v[234:235], s[26:27], 0, v[136:137]
	s_mov_b32 m0, s41
	s_nop 0
	global_load_lds_dwordx4 v[234:235], off
	s_waitcnt vmcnt(8)
	s_waitcnt lgkmcnt(0)
	s_barrier
	s_setprio 3
	s_waitcnt lgkmcnt(0)
	v_mfma_f32_16x16x32_bf16 v[124:127], v[150:153], v[194:197], v[124:127]
	v_mfma_f32_16x16x32_bf16 v[120:123], v[170:173], v[194:197], v[120:123]
	v_mfma_f32_16x16x32_bf16 v[112:115], v[150:153], v[202:205], v[112:115]
	v_mfma_f32_16x16x32_bf16 v[104:107], v[170:173], v[202:205], v[104:107]
	v_mfma_f32_16x16x32_bf16 v[96:99], v[150:153], v[210:213], v[96:99]
	v_mfma_f32_16x16x32_bf16 v[88:91], v[170:173], v[210:213], v[88:91]
	v_mfma_f32_16x16x32_bf16 v[80:83], v[150:153], v[218:221], v[80:83]
	v_mfma_f32_16x16x32_bf16 v[72:75], v[170:173], v[218:221], v[72:75]
	v_mfma_f32_16x16x32_bf16 v[124:127], v[154:157], v[198:201], v[124:127]
	v_mfma_f32_16x16x32_bf16 v[120:123], v[174:177], v[198:201], v[120:123]
	v_mfma_f32_16x16x32_bf16 v[112:115], v[154:157], v[206:209], v[112:115]
	v_mfma_f32_16x16x32_bf16 v[104:107], v[174:177], v[206:209], v[104:107]
	v_mfma_f32_16x16x32_bf16 v[96:99], v[154:157], v[214:217], v[96:99]
	v_mfma_f32_16x16x32_bf16 v[88:91], v[174:177], v[214:217], v[88:91]
	v_mfma_f32_16x16x32_bf16 v[80:83], v[154:157], v[222:225], v[80:83]
	v_mfma_f32_16x16x32_bf16 v[72:75], v[174:177], v[222:225], v[72:75]
	s_setprio 0
	s_setprio 3
	v_mfma_f32_16x16x32_bf16 v[116:119], v[178:181], v[194:197], v[116:119]
	v_mfma_f32_16x16x32_bf16 v[108:111], v[186:189], v[194:197], v[108:111]
	v_mfma_f32_16x16x32_bf16 v[100:103], v[178:181], v[202:205], v[100:103]
	v_mfma_f32_16x16x32_bf16 v[92:95], v[186:189], v[202:205], v[92:95]
	v_mfma_f32_16x16x32_bf16 v[84:87], v[178:181], v[210:213], v[84:87]
	v_mfma_f32_16x16x32_bf16 v[76:79], v[186:189], v[210:213], v[76:79]
	v_mfma_f32_16x16x32_bf16 v[68:71], v[178:181], v[218:221], v[68:71]
	v_mfma_f32_16x16x32_bf16 v[64:67], v[186:189], v[218:221], v[64:67]
	v_mfma_f32_16x16x32_bf16 v[116:119], v[182:185], v[198:201], v[116:119]
	v_mfma_f32_16x16x32_bf16 v[108:111], v[190:193], v[198:201], v[108:111]
	v_mfma_f32_16x16x32_bf16 v[100:103], v[182:185], v[206:209], v[100:103]
	v_mfma_f32_16x16x32_bf16 v[92:95], v[190:193], v[206:209], v[92:95]
	v_mfma_f32_16x16x32_bf16 v[84:87], v[182:185], v[214:217], v[84:87]
	v_mfma_f32_16x16x32_bf16 v[76:79], v[190:193], v[214:217], v[76:79]
	v_mfma_f32_16x16x32_bf16 v[68:71], v[182:185], v[222:225], v[68:71]
	v_mfma_f32_16x16x32_bf16 v[64:67], v[190:193], v[222:225], v[64:67]
	s_setprio 0
	s_barrier
	s_add_i32 s26, s50, s37
	v_lshl_add_u64 v[226:227], v[226:227], 0, s[84:85]
	s_mov_b32 m0, s26
	ds_read_b128 v[194:197], v149 offset:49152
	ds_read_b128 v[198:201], v149 offset:50176
	ds_read_b128 v[202:205], v149 offset:51200
	ds_read_b128 v[206:209], v149 offset:52224
	ds_read_b128 v[210:213], v149 offset:53248
	ds_read_b128 v[214:217], v149 offset:54272
	ds_read_b128 v[218:221], v149 offset:55296
	ds_read_b128 v[222:225], v149 offset:56320
	global_load_lds_dwordx4 v[226:227], off
	s_add_i32 m0, s26, 0x2000
	s_add_u32 s24, s24, 0x40080
	v_lshl_add_u64 v[226:227], v[228:229], 0, s[84:85]
	s_addc_u32 s25, s25, 0
	s_add_i32 s26, s51, s37
	global_load_lds_dwordx4 v[226:227], off
	v_lshl_add_u64 v[226:227], s[24:25], 0, v[128:129]
	s_mov_b32 m0, s26
	s_nop 0
	global_load_lds_dwordx4 v[226:227], off
	v_lshl_add_u64 v[226:227], s[24:25], 0, v[134:135]
	s_add_i32 m0, s26, 0x2000
	s_nop 0
	global_load_lds_dwordx4 v[226:227], off
	v_lshl_add_u64 v[226:227], v[230:231], 0, s[84:85]
	s_mov_b32 m0, s42
	s_nop 0
	global_load_lds_dwordx4 v[226:227], off
	v_lshl_add_u64 v[226:227], v[232:233], 0, s[84:85]
	s_mov_b32 m0, s43
	s_nop 0
	global_load_lds_dwordx4 v[226:227], off
	s_waitcnt vmcnt(8)
	s_waitcnt lgkmcnt(0)
	s_barrier
	s_setprio 3
	s_waitcnt lgkmcnt(0)
	v_mfma_f32_16x16x32_bf16 v[60:63], v[150:153], v[194:197], v[60:63]
	v_mfma_f32_16x16x32_bf16 v[56:59], v[170:173], v[194:197], v[56:59]
	v_mfma_f32_16x16x32_bf16 v[48:51], v[150:153], v[202:205], v[48:51]
	v_mfma_f32_16x16x32_bf16 v[40:43], v[170:173], v[202:205], v[40:43]
	v_mfma_f32_16x16x32_bf16 v[32:35], v[150:153], v[210:213], v[32:35]
	v_mfma_f32_16x16x32_bf16 v[24:27], v[170:173], v[210:213], v[24:27]
	v_mfma_f32_16x16x32_bf16 v[16:19], v[150:153], v[218:221], v[16:19]
	v_mfma_f32_16x16x32_bf16 v[8:11], v[170:173], v[218:221], v[8:11]
	v_mfma_f32_16x16x32_bf16 v[60:63], v[154:157], v[198:201], v[60:63]
	v_mfma_f32_16x16x32_bf16 v[56:59], v[174:177], v[198:201], v[56:59]
	v_mfma_f32_16x16x32_bf16 v[48:51], v[154:157], v[206:209], v[48:51]
	v_mfma_f32_16x16x32_bf16 v[40:43], v[174:177], v[206:209], v[40:43]
	v_mfma_f32_16x16x32_bf16 v[32:35], v[154:157], v[214:217], v[32:35]
	v_mfma_f32_16x16x32_bf16 v[24:27], v[174:177], v[214:217], v[24:27]
	v_mfma_f32_16x16x32_bf16 v[16:19], v[154:157], v[222:225], v[16:19]
	v_mfma_f32_16x16x32_bf16 v[8:11], v[174:177], v[222:225], v[8:11]
	s_setprio 0
	s_setprio 3
	v_mfma_f32_16x16x32_bf16 v[52:55], v[178:181], v[194:197], v[52:55]
	v_mfma_f32_16x16x32_bf16 v[44:47], v[186:189], v[194:197], v[44:47]
	v_mfma_f32_16x16x32_bf16 v[36:39], v[178:181], v[202:205], v[36:39]
	v_mfma_f32_16x16x32_bf16 v[28:31], v[186:189], v[202:205], v[28:31]
	v_mfma_f32_16x16x32_bf16 v[20:23], v[178:181], v[210:213], v[20:23]
	v_mfma_f32_16x16x32_bf16 v[12:15], v[186:189], v[210:213], v[12:15]
	v_mfma_f32_16x16x32_bf16 v[4:7], v[178:181], v[218:221], v[4:7]
	v_mfma_f32_16x16x32_bf16 v[0:3], v[186:189], v[218:221], v[0:3]
	v_mfma_f32_16x16x32_bf16 v[52:55], v[182:185], v[198:201], v[52:55]
	v_mfma_f32_16x16x32_bf16 v[44:47], v[190:193], v[198:201], v[44:47]
	v_mfma_f32_16x16x32_bf16 v[36:39], v[182:185], v[206:209], v[36:39]
	v_mfma_f32_16x16x32_bf16 v[28:31], v[190:193], v[206:209], v[28:31]
	v_mfma_f32_16x16x32_bf16 v[20:23], v[182:185], v[214:217], v[20:23]
	v_mfma_f32_16x16x32_bf16 v[12:15], v[190:193], v[214:217], v[12:15]
	v_mfma_f32_16x16x32_bf16 v[4:7], v[182:185], v[222:225], v[4:7]
	v_mfma_f32_16x16x32_bf16 v[0:3], v[190:193], v[222:225], v[0:3]
	s_setprio 0
	s_barrier
	s_add_i32 s49, s49, 2
	s_add_u32 s20, s20, 0x100
	s_addc_u32 s21, s21, 0
	s_add_u32 s47, s47, 0x100
	s_addc_u32 s48, s48, 0
	s_cmp_gt_u32 s49, 13
	s_branch .LBB0_184
.Lit0_prj_skip:
	s_and_b64 vcc, exec, s[6:7]
	s_cbranch_vccz .LBB0_187
	s_barrier

.LBB0_240:
	s_add_u32 s24, s8, 0x100
	s_addc_u32 s25, s9, 0
	s_add_u32 s8, s10, 0x80
	s_addc_u32 s9, s11, 0
	s_mov_b32 s10, 0
	s_waitcnt lgkmcnt(0)
	s_branch .Lit0_res
.LBB0_241:
	s_add_i32 s39, s10, 2
	s_add_u32 s40, s8, 0x80
	s_addc_u32 s11, s9, 0
	s_add_i32 s42, 0, 0x10000
	s_cmp_eq_u32 s13, s10
	s_cselect_b32 s11, s93, s11
	s_cselect_b32 s10, s92, s40
	v_add_u32_e32 v156, s42, v170
	s_cselect_b32 s41, s95, s25
	s_cselect_b32 s40, s94, s24
	s_add_i32 s43, 0, 0x14000
	ds_read_b128 v[148:151], v156
	ds_read_b128 v[152:155], v156 offset:1024
	ds_read_b128 v[174:177], v156 offset:2048
	ds_read_b128 v[178:181], v156 offset:3072
	v_add_u32_e32 v156, s43, v170
	ds_read_b128 v[182:185], v156
	ds_read_b128 v[186:189], v156 offset:1024
	ds_read_b128 v[190:193], v156 offset:2048
	ds_read_b128 v[194:197], v156 offset:3072
	v_lshl_add_u64 v[156:157], s[8:9], 0, v[146:147]
	s_add_i32 m0, s98, 0xc000
	ds_read_b128 v[198:201], v172
	ds_read_b128 v[202:205], v172 offset:1024
	ds_read_b128 v[206:209], v172 offset:2048
	ds_read_b128 v[210:213], v172 offset:3072
	ds_read_b128 v[214:217], v172 offset:4096
	ds_read_b128 v[218:221], v172 offset:5120
	ds_read_b128 v[222:225], v172 offset:6144
	ds_read_b128 v[226:229], v172 offset:7168
	global_load_lds_dwordx4 v[156:157], off
	v_lshl_add_u64 v[156:157], s[8:9], 0, v[144:145]
	s_add_i32 m0, s98, 0xe000
	s_nop 0
	global_load_lds_dwordx4 v[156:157], off
	s_waitcnt vmcnt(8)
	s_waitcnt lgkmcnt(0)
	s_barrier
	s_setprio 3
	s_waitcnt lgkmcnt(0)
	v_mfma_f32_16x16x32_bf16 v[124:127], v[148:151], v[198:201], v[124:127]
	v_mfma_f32_16x16x32_bf16 v[120:123], v[174:177], v[198:201], v[120:123]
	v_mfma_f32_16x16x32_bf16 v[108:111], v[148:151], v[206:209], v[108:111]
	v_mfma_f32_16x16x32_bf16 v[104:107], v[174:177], v[206:209], v[104:107]
	v_mfma_f32_16x16x32_bf16 v[92:95], v[148:151], v[214:217], v[92:95]
	v_mfma_f32_16x16x32_bf16 v[88:91], v[174:177], v[214:217], v[88:91]
	v_mfma_f32_16x16x32_bf16 v[76:79], v[148:151], v[222:225], v[76:79]
	v_mfma_f32_16x16x32_bf16 v[72:75], v[174:177], v[222:225], v[72:75]
	v_mfma_f32_16x16x32_bf16 v[124:127], v[152:155], v[202:205], v[124:127]
	v_mfma_f32_16x16x32_bf16 v[120:123], v[178:181], v[202:205], v[120:123]
	v_mfma_f32_16x16x32_bf16 v[108:111], v[152:155], v[210:213], v[108:111]
	v_mfma_f32_16x16x32_bf16 v[104:107], v[178:181], v[210:213], v[104:107]
	v_mfma_f32_16x16x32_bf16 v[92:95], v[152:155], v[218:221], v[92:95]
	v_mfma_f32_16x16x32_bf16 v[88:91], v[178:181], v[218:221], v[88:91]
	v_mfma_f32_16x16x32_bf16 v[76:79], v[152:155], v[226:229], v[76:79]
	v_mfma_f32_16x16x32_bf16 v[72:75], v[178:181], v[226:229], v[72:75]
	s_setprio 0
	s_setprio 3
	v_mfma_f32_16x16x32_bf16 v[116:119], v[182:185], v[198:201], v[116:119]
	v_mfma_f32_16x16x32_bf16 v[112:115], v[190:193], v[198:201], v[112:115]
	v_mfma_f32_16x16x32_bf16 v[100:103], v[182:185], v[206:209], v[100:103]
	v_mfma_f32_16x16x32_bf16 v[96:99], v[190:193], v[206:209], v[96:99]
	v_mfma_f32_16x16x32_bf16 v[84:87], v[182:185], v[214:217], v[84:87]
	v_mfma_f32_16x16x32_bf16 v[80:83], v[190:193], v[214:217], v[80:83]
	v_mfma_f32_16x16x32_bf16 v[68:71], v[182:185], v[222:225], v[68:71]
	v_mfma_f32_16x16x32_bf16 v[64:67], v[190:193], v[222:225], v[64:67]
	v_mfma_f32_16x16x32_bf16 v[116:119], v[186:189], v[202:205], v[116:119]
	v_mfma_f32_16x16x32_bf16 v[112:115], v[194:197], v[202:205], v[112:115]
	v_mfma_f32_16x16x32_bf16 v[100:103], v[186:189], v[210:213], v[100:103]
	v_mfma_f32_16x16x32_bf16 v[96:99], v[194:197], v[210:213], v[96:99]
	v_mfma_f32_16x16x32_bf16 v[84:87], v[186:189], v[218:221], v[84:87]
	v_mfma_f32_16x16x32_bf16 v[80:83], v[194:197], v[218:221], v[80:83]
	v_mfma_f32_16x16x32_bf16 v[68:71], v[186:189], v[226:229], v[68:71]
	v_mfma_f32_16x16x32_bf16 v[64:67], v[194:197], v[226:229], v[64:67]
	s_setprio 0
	s_barrier
	s_add_i32 s42, s42, s81
	v_lshl_add_u64 v[156:157], s[40:41], 0, v[128:129]
	s_mov_b32 m0, s42
	ds_read_b128 v[198:201], v172 offset:16384
	ds_read_b128 v[202:205], v172 offset:17408
	ds_read_b128 v[206:209], v172 offset:18432
	ds_read_b128 v[210:213], v172 offset:19456
	ds_read_b128 v[214:217], v172 offset:20480
	ds_read_b128 v[218:221], v172 offset:21504
	ds_read_b128 v[222:225], v172 offset:22528
	ds_read_b128 v[226:229], v172 offset:23552
	global_load_lds_dwordx4 v[156:157], off
	s_add_i32 m0, s42, 0x2000
	v_lshl_add_u64 v[230:231], s[40:41], 0, v[138:139]
	s_add_u32 s40, s40, s0
	s_addc_u32 s41, s41, 0
	s_add_i32 s42, s43, s81
	global_load_lds_dwordx4 v[230:231], off
	v_lshl_add_u64 v[232:233], s[40:41], 0, v[128:129]
	s_mov_b32 m0, s42
	v_lshl_add_u64 v[234:235], s[40:41], 0, v[138:139]
	global_load_lds_dwordx4 v[232:233], off
	s_add_i32 m0, s42, 0x2000
	v_lshl_add_u64 v[236:237], s[10:11], 0, v[134:135]
	global_load_lds_dwordx4 v[234:235], off
	s_mov_b32 m0, s98
	v_lshl_add_u64 v[238:239], s[10:11], 0, v[136:137]
	global_load_lds_dwordx4 v[236:237], off
	s_mov_b32 m0, s99
	s_nop 0
	global_load_lds_dwordx4 v[238:239], off
	s_waitcnt vmcnt(8)
	s_waitcnt lgkmcnt(0)
	s_barrier
	s_setprio 3
	s_waitcnt lgkmcnt(0)
	v_mfma_f32_16x16x32_bf16 v[60:63], v[148:151], v[198:201], v[60:63]
	v_mfma_f32_16x16x32_bf16 v[56:59], v[174:177], v[198:201], v[56:59]
	v_mfma_f32_16x16x32_bf16 v[44:47], v[148:151], v[206:209], v[44:47]
	v_mfma_f32_16x16x32_bf16 v[40:43], v[174:177], v[206:209], v[40:43]
	v_mfma_f32_16x16x32_bf16 v[28:31], v[148:151], v[214:217], v[28:31]
	v_mfma_f32_16x16x32_bf16 v[24:27], v[174:177], v[214:217], v[24:27]
	v_mfma_f32_16x16x32_bf16 v[12:15], v[148:151], v[222:225], v[12:15]
	v_mfma_f32_16x16x32_bf16 v[8:11], v[174:177], v[222:225], v[8:11]
	v_mfma_f32_16x16x32_bf16 v[60:63], v[152:155], v[202:205], v[60:63]
	v_mfma_f32_16x16x32_bf16 v[56:59], v[178:181], v[202:205], v[56:59]
	v_mfma_f32_16x16x32_bf16 v[44:47], v[152:155], v[210:213], v[44:47]
	v_mfma_f32_16x16x32_bf16 v[40:43], v[178:181], v[210:213], v[40:43]
	v_mfma_f32_16x16x32_bf16 v[28:31], v[152:155], v[218:221], v[28:31]
	v_mfma_f32_16x16x32_bf16 v[24:27], v[178:181], v[218:221], v[24:27]
	v_mfma_f32_16x16x32_bf16 v[12:15], v[152:155], v[226:229], v[12:15]
	v_mfma_f32_16x16x32_bf16 v[8:11], v[178:181], v[226:229], v[8:11]
	s_setprio 0
	s_setprio 3
	v_mfma_f32_16x16x32_bf16 v[52:55], v[182:185], v[198:201], v[52:55]
	v_mfma_f32_16x16x32_bf16 v[48:51], v[190:193], v[198:201], v[48:51]
	v_mfma_f32_16x16x32_bf16 v[36:39], v[182:185], v[206:209], v[36:39]
	v_mfma_f32_16x16x32_bf16 v[32:35], v[190:193], v[206:209], v[32:35]
	v_mfma_f32_16x16x32_bf16 v[20:23], v[182:185], v[214:217], v[20:23]
	v_mfma_f32_16x16x32_bf16 v[16:19], v[190:193], v[214:217], v[16:19]
	v_mfma_f32_16x16x32_bf16 v[0:3], v[182:185], v[222:225], v[0:3]
	v_mfma_f32_16x16x32_bf16 v[4:7], v[190:193], v[222:225], v[4:7]
	v_mfma_f32_16x16x32_bf16 v[52:55], v[186:189], v[202:205], v[52:55]
	v_mfma_f32_16x16x32_bf16 v[48:51], v[194:197], v[202:205], v[48:51]
	v_mfma_f32_16x16x32_bf16 v[36:39], v[186:189], v[210:213], v[36:39]
	v_mfma_f32_16x16x32_bf16 v[32:35], v[194:197], v[210:213], v[32:35]
	v_mfma_f32_16x16x32_bf16 v[20:23], v[186:189], v[218:221], v[20:23]
	v_mfma_f32_16x16x32_bf16 v[16:19], v[194:197], v[218:221], v[16:19]
	v_mfma_f32_16x16x32_bf16 v[0:3], v[186:189], v[226:229], v[0:3]
	v_mfma_f32_16x16x32_bf16 v[4:7], v[194:197], v[226:229], v[4:7]
	s_setprio 0
	s_barrier
	s_add_i32 s40, 0, 0x18000
	v_add_u32_e32 v173, s40, v170
	s_add_i32 s41, 0, 0x1c000
	ds_read_b128 v[148:151], v173
	ds_read_b128 v[152:155], v173 offset:1024
	ds_read_b128 v[174:177], v173 offset:2048
	ds_read_b128 v[178:181], v173 offset:3072
	v_add_u32_e32 v173, s41, v170
	ds_read_b128 v[182:185], v173
	ds_read_b128 v[186:189], v173 offset:1024
	ds_read_b128 v[190:193], v173 offset:2048
	ds_read_b128 v[194:197], v173 offset:3072
	s_add_u32 s10, s10, s0
	s_addc_u32 s11, s11, 0
	s_mov_b32 m0, s77
	v_lshl_add_u64 v[240:241], s[10:11], 0, v[134:135]
	ds_read_b128 v[198:201], v172 offset:32768
	ds_read_b128 v[202:205], v172 offset:33792
	ds_read_b128 v[206:209], v172 offset:34816
	ds_read_b128 v[210:213], v172 offset:35840
	ds_read_b128 v[214:217], v172 offset:36864
	ds_read_b128 v[218:221], v172 offset:37888
	ds_read_b128 v[222:225], v172 offset:38912
	ds_read_b128 v[226:229], v172 offset:39936
	global_load_lds_dwordx4 v[240:241], off
	v_lshl_add_u64 v[240:241], s[10:11], 0, v[136:137]
	s_mov_b32 m0, s78
	s_nop 0
	global_load_lds_dwordx4 v[240:241], off
	s_waitcnt vmcnt(8)
	s_waitcnt lgkmcnt(0)
	s_barrier
	s_setprio 3
	s_waitcnt lgkmcnt(0)
	v_mfma_f32_16x16x32_bf16 v[124:127], v[148:151], v[198:201], v[124:127]
	v_mfma_f32_16x16x32_bf16 v[120:123], v[174:177], v[198:201], v[120:123]
	v_mfma_f32_16x16x32_bf16 v[108:111], v[148:151], v[206:209], v[108:111]
	v_mfma_f32_16x16x32_bf16 v[104:107], v[174:177], v[206:209], v[104:107]
	v_mfma_f32_16x16x32_bf16 v[92:95], v[148:151], v[214:217], v[92:95]
	v_mfma_f32_16x16x32_bf16 v[88:91], v[174:177], v[214:217], v[88:91]
	v_mfma_f32_16x16x32_bf16 v[76:79], v[148:151], v[222:225], v[76:79]
	v_mfma_f32_16x16x32_bf16 v[72:75], v[174:177], v[222:225], v[72:75]
	v_mfma_f32_16x16x32_bf16 v[124:127], v[152:155], v[202:205], v[124:127]
	v_mfma_f32_16x16x32_bf16 v[120:123], v[178:181], v[202:205], v[120:123]
	v_mfma_f32_16x16x32_bf16 v[108:111], v[152:155], v[210:213], v[108:111]
	v_mfma_f32_16x16x32_bf16 v[104:107], v[178:181], v[210:213], v[104:107]
	v_mfma_f32_16x16x32_bf16 v[92:95], v[152:155], v[218:221], v[92:95]
	v_mfma_f32_16x16x32_bf16 v[88:91], v[178:181], v[218:221], v[88:91]
	v_mfma_f32_16x16x32_bf16 v[76:79], v[152:155], v[226:229], v[76:79]
	v_mfma_f32_16x16x32_bf16 v[72:75], v[178:181], v[226:229], v[72:75]
	s_setprio 0
	s_setprio 3
	v_mfma_f32_16x16x32_bf16 v[116:119], v[182:185], v[198:201], v[116:119]
	v_mfma_f32_16x16x32_bf16 v[112:115], v[190:193], v[198:201], v[112:115]
	v_mfma_f32_16x16x32_bf16 v[100:103], v[182:185], v[206:209], v[100:103]
	v_mfma_f32_16x16x32_bf16 v[96:99], v[190:193], v[206:209], v[96:99]
	v_mfma_f32_16x16x32_bf16 v[84:87], v[182:185], v[214:217], v[84:87]
	v_mfma_f32_16x16x32_bf16 v[80:83], v[190:193], v[214:217], v[80:83]
	v_mfma_f32_16x16x32_bf16 v[68:71], v[182:185], v[222:225], v[68:71]
	v_mfma_f32_16x16x32_bf16 v[64:67], v[190:193], v[222:225], v[64:67]
	v_mfma_f32_16x16x32_bf16 v[116:119], v[186:189], v[202:205], v[116:119]
	v_mfma_f32_16x16x32_bf16 v[112:115], v[194:197], v[202:205], v[112:115]
	v_mfma_f32_16x16x32_bf16 v[100:103], v[186:189], v[210:213], v[100:103]
	v_mfma_f32_16x16x32_bf16 v[96:99], v[194:197], v[210:213], v[96:99]
	v_mfma_f32_16x16x32_bf16 v[84:87], v[186:189], v[218:221], v[84:87]
	v_mfma_f32_16x16x32_bf16 v[80:83], v[194:197], v[218:221], v[80:83]
	v_mfma_f32_16x16x32_bf16 v[68:71], v[186:189], v[226:229], v[68:71]
	v_mfma_f32_16x16x32_bf16 v[64:67], v[194:197], v[226:229], v[64:67]
	s_setprio 0
	s_barrier
	s_add_i32 s10, s40, s81
	v_lshl_add_u64 v[156:157], v[156:157], 0, s[84:85]
	s_mov_b32 m0, s10
	ds_read_b128 v[198:201], v172 offset:49152
	ds_read_b128 v[202:205], v172 offset:50176
	ds_read_b128 v[206:209], v172 offset:51200
	ds_read_b128 v[210:213], v172 offset:52224
	ds_read_b128 v[214:217], v172 offset:53248
	ds_read_b128 v[218:221], v172 offset:54272
	ds_read_b128 v[222:225], v172 offset:55296
	ds_read_b128 v[226:229], v172 offset:56320
	global_load_lds_dwordx4 v[156:157], off
	v_lshl_add_u64 v[156:157], v[230:231], 0, s[84:85]
	s_add_i32 m0, s10, 0x2000
	s_add_i32 s10, s41, s81
	global_load_lds_dwordx4 v[156:157], off
	v_lshl_add_u64 v[156:157], v[232:233], 0, s[84:85]
	s_mov_b32 m0, s10
	s_nop 0
	global_load_lds_dwordx4 v[156:157], off
	v_lshl_add_u64 v[156:157], v[234:235], 0, s[84:85]
	s_add_i32 m0, s10, 0x2000
	s_nop 0
	global_load_lds_dwordx4 v[156:157], off
	v_lshl_add_u64 v[156:157], v[236:237], 0, s[84:85]
	s_mov_b32 m0, s79
	s_nop 0
	global_load_lds_dwordx4 v[156:157], off
	v_lshl_add_u64 v[156:157], v[238:239], 0, s[84:85]
	s_mov_b32 m0, s90
	s_nop 0
	global_load_lds_dwordx4 v[156:157], off
	s_waitcnt vmcnt(8)
	s_waitcnt lgkmcnt(0)
	s_barrier
	s_setprio 3
	s_waitcnt lgkmcnt(0)
	v_mfma_f32_16x16x32_bf16 v[60:63], v[148:151], v[198:201], v[60:63]
	v_mfma_f32_16x16x32_bf16 v[56:59], v[174:177], v[198:201], v[56:59]
	v_mfma_f32_16x16x32_bf16 v[44:47], v[148:151], v[206:209], v[44:47]
	v_mfma_f32_16x16x32_bf16 v[40:43], v[174:177], v[206:209], v[40:43]
	v_mfma_f32_16x16x32_bf16 v[28:31], v[148:151], v[214:217], v[28:31]
	v_mfma_f32_16x16x32_bf16 v[24:27], v[174:177], v[214:217], v[24:27]
	v_mfma_f32_16x16x32_bf16 v[12:15], v[148:151], v[222:225], v[12:15]
	v_mfma_f32_16x16x32_bf16 v[8:11], v[174:177], v[222:225], v[8:11]
	v_mfma_f32_16x16x32_bf16 v[60:63], v[152:155], v[202:205], v[60:63]
	v_mfma_f32_16x16x32_bf16 v[56:59], v[178:181], v[202:205], v[56:59]
	v_mfma_f32_16x16x32_bf16 v[44:47], v[152:155], v[210:213], v[44:47]
	v_mfma_f32_16x16x32_bf16 v[40:43], v[178:181], v[210:213], v[40:43]
	v_mfma_f32_16x16x32_bf16 v[28:31], v[152:155], v[218:221], v[28:31]
	v_mfma_f32_16x16x32_bf16 v[24:27], v[178:181], v[218:221], v[24:27]
	v_mfma_f32_16x16x32_bf16 v[12:15], v[152:155], v[226:229], v[12:15]
	v_mfma_f32_16x16x32_bf16 v[8:11], v[178:181], v[226:229], v[8:11]
	s_setprio 0
	s_setprio 3
	v_mfma_f32_16x16x32_bf16 v[52:55], v[182:185], v[198:201], v[52:55]
	v_mfma_f32_16x16x32_bf16 v[48:51], v[190:193], v[198:201], v[48:51]
	v_mfma_f32_16x16x32_bf16 v[36:39], v[182:185], v[206:209], v[36:39]
	v_mfma_f32_16x16x32_bf16 v[32:35], v[190:193], v[206:209], v[32:35]
	v_mfma_f32_16x16x32_bf16 v[20:23], v[182:185], v[214:217], v[20:23]
	v_mfma_f32_16x16x32_bf16 v[16:19], v[190:193], v[214:217], v[16:19]
	v_mfma_f32_16x16x32_bf16 v[0:3], v[182:185], v[222:225], v[0:3]
	v_mfma_f32_16x16x32_bf16 v[4:7], v[190:193], v[222:225], v[4:7]
	v_mfma_f32_16x16x32_bf16 v[52:55], v[186:189], v[202:205], v[52:55]
	v_mfma_f32_16x16x32_bf16 v[48:51], v[194:197], v[202:205], v[48:51]
	v_mfma_f32_16x16x32_bf16 v[36:39], v[186:189], v[210:213], v[36:39]
	v_mfma_f32_16x16x32_bf16 v[32:35], v[194:197], v[210:213], v[32:35]
	v_mfma_f32_16x16x32_bf16 v[20:23], v[186:189], v[218:221], v[20:23]
	v_mfma_f32_16x16x32_bf16 v[16:19], v[194:197], v[218:221], v[16:19]
	v_mfma_f32_16x16x32_bf16 v[0:3], v[186:189], v[226:229], v[0:3]
	v_mfma_f32_16x16x32_bf16 v[4:7], v[194:197], v[226:229], v[4:7]
	s_setprio 0
	s_barrier
	s_add_u32 s24, s24, 0x100
	s_addc_u32 s25, s25, 0
	s_add_u32 s8, s8, 0x100
	s_addc_u32 s9, s9, 0
	s_cmp_ge_u32 s39, s26
	s_mov_b32 s10, s39
	s_cbranch_scc0 .LBB0_241
	s_branch .Lit0_res_skip
.Lit0_res:
	s_add_i32 s39, s10, 2
	s_add_u32 s40, s8, 0x80
	s_addc_u32 s11, s9, 0
	s_add_i32 s42, 0, 0x10000
	s_cmp_eq_u32 s13, s10
	s_cselect_b32 s11, s93, s11
	s_cselect_b32 s10, s92, s40
	v_add_u32_e32 v156, s42, v170
	s_cselect_b32 s41, s95, s25
	s_cselect_b32 s40, s94, s24
	s_add_i32 s43, 0, 0x14000
	ds_read_b128 v[148:151], v156
	ds_read_b128 v[152:155], v156 offset:1024
	ds_read_b128 v[174:177], v156 offset:2048
	ds_read_b128 v[178:181], v156 offset:3072
	v_add_u32_e32 v156, s43, v170
	ds_read_b128 v[182:185], v156
	ds_read_b128 v[186:189], v156 offset:1024
	ds_read_b128 v[190:193], v156 offset:2048
	ds_read_b128 v[194:197], v156 offset:3072
	v_lshl_add_u64 v[156:157], s[8:9], 0, v[146:147]
	s_add_i32 m0, s98, 0xc000
	ds_read_b128 v[198:201], v172
	ds_read_b128 v[202:205], v172 offset:1024
	ds_read_b128 v[206:209], v172 offset:2048
	ds_read_b128 v[210:213], v172 offset:3072
	ds_read_b128 v[214:217], v172 offset:4096
	ds_read_b128 v[218:221], v172 offset:5120
	ds_read_b128 v[222:225], v172 offset:6144
	ds_read_b128 v[226:229], v172 offset:7168
	global_load_lds_dwordx4 v[156:157], off
	v_lshl_add_u64 v[156:157], s[8:9], 0, v[144:145]
	s_add_i32 m0, s98, 0xe000
	s_nop 0
	global_load_lds_dwordx4 v[156:157], off
	s_waitcnt vmcnt(8)
	s_waitcnt lgkmcnt(0)
	s_barrier
	s_setprio 3
	s_waitcnt lgkmcnt(0)
	v_mfma_f32_16x16x32_bf16 v[124:127], v[148:151], v[198:201], 0
	v_mfma_f32_16x16x32_bf16 v[120:123], v[174:177], v[198:201], 0
	v_mfma_f32_16x16x32_bf16 v[108:111], v[148:151], v[206:209], 0
	v_mfma_f32_16x16x32_bf16 v[104:107], v[174:177], v[206:209], 0
	v_mfma_f32_16x16x32_bf16 v[92:95], v[148:151], v[214:217], 0
	v_mfma_f32_16x16x32_bf16 v[88:91], v[174:177], v[214:217], 0
	v_mfma_f32_16x16x32_bf16 v[76:79], v[148:151], v[222:225], 0
	v_mfma_f32_16x16x32_bf16 v[72:75], v[174:177], v[222:225], 0
	v_mfma_f32_16x16x32_bf16 v[124:127], v[152:155], v[202:205], v[124:127]
	v_mfma_f32_16x16x32_bf16 v[120:123], v[178:181], v[202:205], v[120:123]
	v_mfma_f32_16x16x32_bf16 v[108:111], v[152:155], v[210:213], v[108:111]
	v_mfma_f32_16x16x32_bf16 v[104:107], v[178:181], v[210:213], v[104:107]
	v_mfma_f32_16x16x32_bf16 v[92:95], v[152:155], v[218:221], v[92:95]
	v_mfma_f32_16x16x32_bf16 v[88:91], v[178:181], v[218:221], v[88:91]
	v_mfma_f32_16x16x32_bf16 v[76:79], v[152:155], v[226:229], v[76:79]
	v_mfma_f32_16x16x32_bf16 v[72:75], v[178:181], v[226:229], v[72:75]
	s_setprio 0
	s_setprio 3
	v_mfma_f32_16x16x32_bf16 v[116:119], v[182:185], v[198:201], 0
	v_mfma_f32_16x16x32_bf16 v[112:115], v[190:193], v[198:201], 0
	v_mfma_f32_16x16x32_bf16 v[100:103], v[182:185], v[206:209], 0
	v_mfma_f32_16x16x32_bf16 v[96:99], v[190:193], v[206:209], 0
	v_mfma_f32_16x16x32_bf16 v[84:87], v[182:185], v[214:217], 0
	v_mfma_f32_16x16x32_bf16 v[80:83], v[190:193], v[214:217], 0
	v_mfma_f32_16x16x32_bf16 v[68:71], v[182:185], v[222:225], 0
	v_mfma_f32_16x16x32_bf16 v[64:67], v[190:193], v[222:225], 0
	v_mfma_f32_16x16x32_bf16 v[116:119], v[186:189], v[202:205], v[116:119]
	v_mfma_f32_16x16x32_bf16 v[112:115], v[194:197], v[202:205], v[112:115]
	v_mfma_f32_16x16x32_bf16 v[100:103], v[186:189], v[210:213], v[100:103]
	v_mfma_f32_16x16x32_bf16 v[96:99], v[194:197], v[210:213], v[96:99]
	v_mfma_f32_16x16x32_bf16 v[84:87], v[186:189], v[218:221], v[84:87]
	v_mfma_f32_16x16x32_bf16 v[80:83], v[194:197], v[218:221], v[80:83]
	v_mfma_f32_16x16x32_bf16 v[68:71], v[186:189], v[226:229], v[68:71]
	v_mfma_f32_16x16x32_bf16 v[64:67], v[194:197], v[226:229], v[64:67]
	s_setprio 0
	s_barrier
	s_add_i32 s42, s42, s81
	v_lshl_add_u64 v[156:157], s[40:41], 0, v[128:129]
	s_mov_b32 m0, s42
	ds_read_b128 v[198:201], v172 offset:16384
	ds_read_b128 v[202:205], v172 offset:17408
	ds_read_b128 v[206:209], v172 offset:18432
	ds_read_b128 v[210:213], v172 offset:19456
	ds_read_b128 v[214:217], v172 offset:20480
	ds_read_b128 v[218:221], v172 offset:21504
	ds_read_b128 v[222:225], v172 offset:22528
	ds_read_b128 v[226:229], v172 offset:23552
	global_load_lds_dwordx4 v[156:157], off
	s_add_i32 m0, s42, 0x2000
	v_lshl_add_u64 v[230:231], s[40:41], 0, v[138:139]
	s_add_u32 s40, s40, s0
	s_addc_u32 s41, s41, 0
	s_add_i32 s42, s43, s81
	global_load_lds_dwordx4 v[230:231], off
	v_lshl_add_u64 v[232:233], s[40:41], 0, v[128:129]
	s_mov_b32 m0, s42
	v_lshl_add_u64 v[234:235], s[40:41], 0, v[138:139]
	global_load_lds_dwordx4 v[232:233], off
	s_add_i32 m0, s42, 0x2000
	v_lshl_add_u64 v[236:237], s[10:11], 0, v[134:135]
	global_load_lds_dwordx4 v[234:235], off
	s_mov_b32 m0, s98
	v_lshl_add_u64 v[238:239], s[10:11], 0, v[136:137]
	global_load_lds_dwordx4 v[236:237], off
	s_mov_b32 m0, s99
	s_nop 0
	global_load_lds_dwordx4 v[238:239], off
	s_waitcnt vmcnt(8)
	s_waitcnt lgkmcnt(0)
	s_barrier
	s_setprio 3
	s_waitcnt lgkmcnt(0)
	v_mfma_f32_16x16x32_bf16 v[60:63], v[148:151], v[198:201], 0
	v_mfma_f32_16x16x32_bf16 v[56:59], v[174:177], v[198:201], 0
	v_mfma_f32_16x16x32_bf16 v[44:47], v[148:151], v[206:209], 0
	v_mfma_f32_16x16x32_bf16 v[40:43], v[174:177], v[206:209], 0
	v_mfma_f32_16x16x32_bf16 v[28:31], v[148:151], v[214:217], 0
	v_mfma_f32_16x16x32_bf16 v[24:27], v[174:177], v[214:217], 0
	v_mfma_f32_16x16x32_bf16 v[12:15], v[148:151], v[222:225], 0
	v_mfma_f32_16x16x32_bf16 v[8:11], v[174:177], v[222:225], 0
	v_mfma_f32_16x16x32_bf16 v[60:63], v[152:155], v[202:205], v[60:63]
	v_mfma_f32_16x16x32_bf16 v[56:59], v[178:181], v[202:205], v[56:59]
	v_mfma_f32_16x16x32_bf16 v[44:47], v[152:155], v[210:213], v[44:47]
	v_mfma_f32_16x16x32_bf16 v[40:43], v[178:181], v[210:213], v[40:43]
	v_mfma_f32_16x16x32_bf16 v[28:31], v[152:155], v[218:221], v[28:31]
	v_mfma_f32_16x16x32_bf16 v[24:27], v[178:181], v[218:221], v[24:27]
	v_mfma_f32_16x16x32_bf16 v[12:15], v[152:155], v[226:229], v[12:15]
	v_mfma_f32_16x16x32_bf16 v[8:11], v[178:181], v[226:229], v[8:11]
	s_setprio 0
	s_setprio 3
	v_mfma_f32_16x16x32_bf16 v[52:55], v[182:185], v[198:201], 0
	v_mfma_f32_16x16x32_bf16 v[48:51], v[190:193], v[198:201], 0
	v_mfma_f32_16x16x32_bf16 v[36:39], v[182:185], v[206:209], 0
	v_mfma_f32_16x16x32_bf16 v[32:35], v[190:193], v[206:209], 0
	v_mfma_f32_16x16x32_bf16 v[20:23], v[182:185], v[214:217], 0
	v_mfma_f32_16x16x32_bf16 v[16:19], v[190:193], v[214:217], 0
	v_mfma_f32_16x16x32_bf16 v[0:3], v[182:185], v[222:225], 0
	v_mfma_f32_16x16x32_bf16 v[4:7], v[190:193], v[222:225], 0
	v_mfma_f32_16x16x32_bf16 v[52:55], v[186:189], v[202:205], v[52:55]
	v_mfma_f32_16x16x32_bf16 v[48:51], v[194:197], v[202:205], v[48:51]
	v_mfma_f32_16x16x32_bf16 v[36:39], v[186:189], v[210:213], v[36:39]
	v_mfma_f32_16x16x32_bf16 v[32:35], v[194:197], v[210:213], v[32:35]
	v_mfma_f32_16x16x32_bf16 v[20:23], v[186:189], v[218:221], v[20:23]
	v_mfma_f32_16x16x32_bf16 v[16:19], v[194:197], v[218:221], v[16:19]
	v_mfma_f32_16x16x32_bf16 v[0:3], v[186:189], v[226:229], v[0:3]
	v_mfma_f32_16x16x32_bf16 v[4:7], v[194:197], v[226:229], v[4:7]
	s_setprio 0
	s_barrier
	s_add_i32 s40, 0, 0x18000
	v_add_u32_e32 v173, s40, v170
	s_add_i32 s41, 0, 0x1c000
	ds_read_b128 v[148:151], v173
	ds_read_b128 v[152:155], v173 offset:1024
	ds_read_b128 v[174:177], v173 offset:2048
	ds_read_b128 v[178:181], v173 offset:3072
	v_add_u32_e32 v173, s41, v170
	ds_read_b128 v[182:185], v173
	ds_read_b128 v[186:189], v173 offset:1024
	ds_read_b128 v[190:193], v173 offset:2048
	ds_read_b128 v[194:197], v173 offset:3072
	s_add_u32 s10, s10, s0
	s_addc_u32 s11, s11, 0
	s_mov_b32 m0, s77
	v_lshl_add_u64 v[240:241], s[10:11], 0, v[134:135]
	ds_read_b128 v[198:201], v172 offset:32768
	ds_read_b128 v[202:205], v172 offset:33792
	ds_read_b128 v[206:209], v172 offset:34816
	ds_read_b128 v[210:213], v172 offset:35840
	ds_read_b128 v[214:217], v172 offset:36864
	ds_read_b128 v[218:221], v172 offset:37888
	ds_read_b128 v[222:225], v172 offset:38912
	ds_read_b128 v[226:229], v172 offset:39936
	global_load_lds_dwordx4 v[240:241], off
	v_lshl_add_u64 v[240:241], s[10:11], 0, v[136:137]
	s_mov_b32 m0, s78
	s_nop 0
	global_load_lds_dwordx4 v[240:241], off
	s_waitcnt vmcnt(8)
	s_waitcnt lgkmcnt(0)
	s_barrier
	s_setprio 3
	s_waitcnt lgkmcnt(0)
	v_mfma_f32_16x16x32_bf16 v[124:127], v[148:151], v[198:201], v[124:127]
	v_mfma_f32_16x16x32_bf16 v[120:123], v[174:177], v[198:201], v[120:123]
	v_mfma_f32_16x16x32_bf16 v[108:111], v[148:151], v[206:209], v[108:111]
	v_mfma_f32_16x16x32_bf16 v[104:107], v[174:177], v[206:209], v[104:107]
	v_mfma_f32_16x16x32_bf16 v[92:95], v[148:151], v[214:217], v[92:95]
	v_mfma_f32_16x16x32_bf16 v[88:91], v[174:177], v[214:217], v[88:91]
	v_mfma_f32_16x16x32_bf16 v[76:79], v[148:151], v[222:225], v[76:79]
	v_mfma_f32_16x16x32_bf16 v[72:75], v[174:177], v[222:225], v[72:75]
	v_mfma_f32_16x16x32_bf16 v[124:127], v[152:155], v[202:205], v[124:127]
	v_mfma_f32_16x16x32_bf16 v[120:123], v[178:181], v[202:205], v[120:123]
	v_mfma_f32_16x16x32_bf16 v[108:111], v[152:155], v[210:213], v[108:111]
	v_mfma_f32_16x16x32_bf16 v[104:107], v[178:181], v[210:213], v[104:107]
	v_mfma_f32_16x16x32_bf16 v[92:95], v[152:155], v[218:221], v[92:95]
	v_mfma_f32_16x16x32_bf16 v[88:91], v[178:181], v[218:221], v[88:91]
	v_mfma_f32_16x16x32_bf16 v[76:79], v[152:155], v[226:229], v[76:79]
	v_mfma_f32_16x16x32_bf16 v[72:75], v[178:181], v[226:229], v[72:75]
	s_setprio 0
	s_setprio 3
	v_mfma_f32_16x16x32_bf16 v[116:119], v[182:185], v[198:201], v[116:119]
	v_mfma_f32_16x16x32_bf16 v[112:115], v[190:193], v[198:201], v[112:115]
	v_mfma_f32_16x16x32_bf16 v[100:103], v[182:185], v[206:209], v[100:103]
	v_mfma_f32_16x16x32_bf16 v[96:99], v[190:193], v[206:209], v[96:99]
	v_mfma_f32_16x16x32_bf16 v[84:87], v[182:185], v[214:217], v[84:87]
	v_mfma_f32_16x16x32_bf16 v[80:83], v[190:193], v[214:217], v[80:83]
	v_mfma_f32_16x16x32_bf16 v[68:71], v[182:185], v[222:225], v[68:71]
	v_mfma_f32_16x16x32_bf16 v[64:67], v[190:193], v[222:225], v[64:67]
	v_mfma_f32_16x16x32_bf16 v[116:119], v[186:189], v[202:205], v[116:119]
	v_mfma_f32_16x16x32_bf16 v[112:115], v[194:197], v[202:205], v[112:115]
	v_mfma_f32_16x16x32_bf16 v[100:103], v[186:189], v[210:213], v[100:103]
	v_mfma_f32_16x16x32_bf16 v[96:99], v[194:197], v[210:213], v[96:99]
	v_mfma_f32_16x16x32_bf16 v[84:87], v[186:189], v[218:221], v[84:87]
	v_mfma_f32_16x16x32_bf16 v[80:83], v[194:197], v[218:221], v[80:83]
	v_mfma_f32_16x16x32_bf16 v[68:71], v[186:189], v[226:229], v[68:71]
	v_mfma_f32_16x16x32_bf16 v[64:67], v[194:197], v[226:229], v[64:67]
	s_setprio 0
	s_barrier
	s_add_i32 s10, s40, s81
	v_lshl_add_u64 v[156:157], v[156:157], 0, s[84:85]
	s_mov_b32 m0, s10
	ds_read_b128 v[198:201], v172 offset:49152
	ds_read_b128 v[202:205], v172 offset:50176
	ds_read_b128 v[206:209], v172 offset:51200
	ds_read_b128 v[210:213], v172 offset:52224
	ds_read_b128 v[214:217], v172 offset:53248
	ds_read_b128 v[218:221], v172 offset:54272
	ds_read_b128 v[222:225], v172 offset:55296
	ds_read_b128 v[226:229], v172 offset:56320
	global_load_lds_dwordx4 v[156:157], off
	v_lshl_add_u64 v[156:157], v[230:231], 0, s[84:85]
	s_add_i32 m0, s10, 0x2000
	s_add_i32 s10, s41, s81
	global_load_lds_dwordx4 v[156:157], off
	v_lshl_add_u64 v[156:157], v[232:233], 0, s[84:85]
	s_mov_b32 m0, s10
	s_nop 0
	global_load_lds_dwordx4 v[156:157], off
	v_lshl_add_u64 v[156:157], v[234:235], 0, s[84:85]
	s_add_i32 m0, s10, 0x2000
	s_nop 0
	global_load_lds_dwordx4 v[156:157], off
	v_lshl_add_u64 v[156:157], v[236:237], 0, s[84:85]
	s_mov_b32 m0, s79
	s_nop 0
	global_load_lds_dwordx4 v[156:157], off
	v_lshl_add_u64 v[156:157], v[238:239], 0, s[84:85]
	s_mov_b32 m0, s90
	s_nop 0
	global_load_lds_dwordx4 v[156:157], off
	s_waitcnt vmcnt(8)
	s_waitcnt lgkmcnt(0)
	s_barrier
	s_setprio 3
	s_waitcnt lgkmcnt(0)
	v_mfma_f32_16x16x32_bf16 v[60:63], v[148:151], v[198:201], v[60:63]
	v_mfma_f32_16x16x32_bf16 v[56:59], v[174:177], v[198:201], v[56:59]
	v_mfma_f32_16x16x32_bf16 v[44:47], v[148:151], v[206:209], v[44:47]
	v_mfma_f32_16x16x32_bf16 v[40:43], v[174:177], v[206:209], v[40:43]
	v_mfma_f32_16x16x32_bf16 v[28:31], v[148:151], v[214:217], v[28:31]
	v_mfma_f32_16x16x32_bf16 v[24:27], v[174:177], v[214:217], v[24:27]
	v_mfma_f32_16x16x32_bf16 v[12:15], v[148:151], v[222:225], v[12:15]
	v_mfma_f32_16x16x32_bf16 v[8:11], v[174:177], v[222:225], v[8:11]
	v_mfma_f32_16x16x32_bf16 v[60:63], v[152:155], v[202:205], v[60:63]
	v_mfma_f32_16x16x32_bf16 v[56:59], v[178:181], v[202:205], v[56:59]
	v_mfma_f32_16x16x32_bf16 v[44:47], v[152:155], v[210:213], v[44:47]
	v_mfma_f32_16x16x32_bf16 v[40:43], v[178:181], v[210:213], v[40:43]
	v_mfma_f32_16x16x32_bf16 v[28:31], v[152:155], v[218:221], v[28:31]
	v_mfma_f32_16x16x32_bf16 v[24:27], v[178:181], v[218:221], v[24:27]
	v_mfma_f32_16x16x32_bf16 v[12:15], v[152:155], v[226:229], v[12:15]
	v_mfma_f32_16x16x32_bf16 v[8:11], v[178:181], v[226:229], v[8:11]
	s_setprio 0
	s_setprio 3
	v_mfma_f32_16x16x32_bf16 v[52:55], v[182:185], v[198:201], v[52:55]
	v_mfma_f32_16x16x32_bf16 v[48:51], v[190:193], v[198:201], v[48:51]
	v_mfma_f32_16x16x32_bf16 v[36:39], v[182:185], v[206:209], v[36:39]
	v_mfma_f32_16x16x32_bf16 v[32:35], v[190:193], v[206:209], v[32:35]
	v_mfma_f32_16x16x32_bf16 v[20:23], v[182:185], v[214:217], v[20:23]
	v_mfma_f32_16x16x32_bf16 v[16:19], v[190:193], v[214:217], v[16:19]
	v_mfma_f32_16x16x32_bf16 v[0:3], v[182:185], v[222:225], v[0:3]
	v_mfma_f32_16x16x32_bf16 v[4:7], v[190:193], v[222:225], v[4:7]
	v_mfma_f32_16x16x32_bf16 v[52:55], v[186:189], v[202:205], v[52:55]
	v_mfma_f32_16x16x32_bf16 v[48:51], v[194:197], v[202:205], v[48:51]
	v_mfma_f32_16x16x32_bf16 v[36:39], v[186:189], v[210:213], v[36:39]
	v_mfma_f32_16x16x32_bf16 v[32:35], v[194:197], v[210:213], v[32:35]
	v_mfma_f32_16x16x32_bf16 v[20:23], v[186:189], v[218:221], v[20:23]
	v_mfma_f32_16x16x32_bf16 v[16:19], v[194:197], v[218:221], v[16:19]
	v_mfma_f32_16x16x32_bf16 v[0:3], v[186:189], v[226:229], v[0:3]
	v_mfma_f32_16x16x32_bf16 v[4:7], v[194:197], v[226:229], v[4:7]
	s_setprio 0
	s_barrier
	s_add_u32 s24, s24, 0x100
	s_addc_u32 s25, s25, 0
	s_add_u32 s8, s8, 0x100
	s_addc_u32 s9, s9, 0
	s_cmp_ge_u32 s39, s26
	s_mov_b32 s10, s39
	s_branch .LBB0_241
.Lit0_res_skip:
	s_and_b64 vcc, exec, s[16:17]
	s_cbranch_vccz .LBB0_244
	s_barrier

.LBB0_354:
	s_ashr_i32 s9, s8, 31
	s_lshl_b64 s[14:15], s[8:9], 19
	s_add_u32 s14, s34, s14
	s_addc_u32 s15, s35, s15
	s_and_b64 s[16:17], s[12:13], exec
	s_cselect_b32 s9, s15, s21
	s_cselect_b32 s19, s14, s20
	s_ashr_i32 s11, s10, 31
	s_lshl_b64 s[16:17], s[10:11], 19
	s_add_u32 s16, s22, s16
	s_addc_u32 s17, s36, s17
	s_and_b64 s[26:27], s[12:13], exec
	s_cselect_b32 s11, s17, s25
	s_cselect_b32 s46, s16, s24
	s_add_u32 s20, s20, 0x40080
	s_addc_u32 s21, s21, 0
	s_add_u32 s47, s24, 0x100
	s_addc_u32 s48, s25, 0
	s_mov_b32 s49, -2
	s_branch .Lit0_swi
.LBB0_355:
	s_add_u32 s24, s20, 0xfffc0080
	s_addc_u32 s25, s21, -1
	s_add_i32 s50, 0, 0x10000
	s_cmp_eq_u32 s49, 12
	s_cselect_b32 s27, s9, s25
	s_cselect_b32 s26, s19, s24
	v_add_u32_e32 v144, s50, v146
	s_cselect_b32 s25, s11, s48
	s_cselect_b32 s24, s46, s47
	s_add_i32 s77, 0, 0x14000
	ds_read_b128 v[152:155], v144
	ds_read_b128 v[170:173], v144 offset:1024
	ds_read_b128 v[174:177], v144 offset:2048
	ds_read_b128 v[178:181], v144 offset:3072
	v_add_u32_e32 v144, s77, v146
	ds_read_b128 v[182:185], v144
	ds_read_b128 v[186:189], v144 offset:1024
	ds_read_b128 v[190:193], v144 offset:2048
	ds_read_b128 v[194:197], v144 offset:3072
	v_lshl_add_u64 v[144:145], s[20:21], 0, v[140:141]
	s_add_i32 m0, s38, 0xc000
	ds_read_b128 v[198:201], v150
	ds_read_b128 v[202:205], v150 offset:1024
	ds_read_b128 v[206:209], v150 offset:2048
	ds_read_b128 v[210:213], v150 offset:3072
	ds_read_b128 v[214:217], v150 offset:4096
	ds_read_b128 v[218:221], v150 offset:5120
	ds_read_b128 v[222:225], v150 offset:6144
	ds_read_b128 v[226:229], v150 offset:7168
	global_load_lds_dwordx4 v[144:145], off
	v_lshl_add_u64 v[144:145], s[20:21], 0, v[142:143]
	s_add_i32 m0, s38, 0xe000
	s_nop 0
	global_load_lds_dwordx4 v[144:145], off
	s_waitcnt vmcnt(8)
	s_waitcnt lgkmcnt(0)
	s_barrier
	s_setprio 3
	s_waitcnt lgkmcnt(0)
	v_mfma_f32_16x16x32_bf16 v[124:127], v[152:155], v[198:201], v[124:127]
	v_mfma_f32_16x16x32_bf16 v[116:119], v[174:177], v[198:201], v[116:119]
	v_mfma_f32_16x16x32_bf16 v[108:111], v[152:155], v[206:209], v[108:111]
	v_mfma_f32_16x16x32_bf16 v[100:103], v[174:177], v[206:209], v[100:103]
	v_mfma_f32_16x16x32_bf16 v[92:95], v[152:155], v[214:217], v[92:95]
	v_mfma_f32_16x16x32_bf16 v[84:87], v[174:177], v[214:217], v[84:87]
	v_mfma_f32_16x16x32_bf16 v[76:79], v[152:155], v[222:225], v[76:79]
	v_mfma_f32_16x16x32_bf16 v[68:71], v[174:177], v[222:225], v[68:71]
	v_mfma_f32_16x16x32_bf16 v[124:127], v[170:173], v[202:205], v[124:127]
	v_mfma_f32_16x16x32_bf16 v[116:119], v[178:181], v[202:205], v[116:119]
	v_mfma_f32_16x16x32_bf16 v[108:111], v[170:173], v[210:213], v[108:111]
	v_mfma_f32_16x16x32_bf16 v[100:103], v[178:181], v[210:213], v[100:103]
	v_mfma_f32_16x16x32_bf16 v[92:95], v[170:173], v[218:221], v[92:95]
	v_mfma_f32_16x16x32_bf16 v[84:87], v[178:181], v[218:221], v[84:87]
	v_mfma_f32_16x16x32_bf16 v[76:79], v[170:173], v[226:229], v[76:79]
	v_mfma_f32_16x16x32_bf16 v[68:71], v[178:181], v[226:229], v[68:71]
	s_setprio 0
	s_setprio 3
	v_mfma_f32_16x16x32_bf16 v[120:123], v[182:185], v[198:201], v[120:123]
	v_mfma_f32_16x16x32_bf16 v[112:115], v[190:193], v[198:201], v[112:115]
	v_mfma_f32_16x16x32_bf16 v[104:107], v[182:185], v[206:209], v[104:107]
	v_mfma_f32_16x16x32_bf16 v[96:99], v[190:193], v[206:209], v[96:99]
	v_mfma_f32_16x16x32_bf16 v[88:91], v[182:185], v[214:217], v[88:91]
	v_mfma_f32_16x16x32_bf16 v[80:83], v[190:193], v[214:217], v[80:83]
	v_mfma_f32_16x16x32_bf16 v[72:75], v[182:185], v[222:225], v[72:75]
	v_mfma_f32_16x16x32_bf16 v[64:67], v[190:193], v[222:225], v[64:67]
	v_mfma_f32_16x16x32_bf16 v[120:123], v[186:189], v[202:205], v[120:123]
	v_mfma_f32_16x16x32_bf16 v[112:115], v[194:197], v[202:205], v[112:115]
	v_mfma_f32_16x16x32_bf16 v[104:107], v[186:189], v[210:213], v[104:107]
	v_mfma_f32_16x16x32_bf16 v[96:99], v[194:197], v[210:213], v[96:99]
	v_mfma_f32_16x16x32_bf16 v[88:91], v[186:189], v[218:221], v[88:91]
	v_mfma_f32_16x16x32_bf16 v[80:83], v[194:197], v[218:221], v[80:83]
	v_mfma_f32_16x16x32_bf16 v[72:75], v[186:189], v[226:229], v[72:75]
	v_mfma_f32_16x16x32_bf16 v[64:67], v[194:197], v[226:229], v[64:67]
	s_setprio 0
	s_barrier
	s_add_i32 s50, s50, s37
	v_lshl_add_u64 v[144:145], s[24:25], 0, v[128:129]
	s_mov_b32 m0, s50
	ds_read_b128 v[198:201], v150 offset:16384
	ds_read_b128 v[202:205], v150 offset:17408
	ds_read_b128 v[206:209], v150 offset:18432
	ds_read_b128 v[210:213], v150 offset:19456
	ds_read_b128 v[214:217], v150 offset:20480
	ds_read_b128 v[218:221], v150 offset:21504
	ds_read_b128 v[222:225], v150 offset:22528
	ds_read_b128 v[226:229], v150 offset:23552
	global_load_lds_dwordx4 v[144:145], off
	s_add_i32 m0, s50, 0x2000
	s_add_u32 s50, s24, 0x40000
	v_lshl_add_u64 v[156:157], s[24:25], 0, v[134:135]
	s_addc_u32 s51, s25, 0
	s_add_i32 s77, s77, s37
	global_load_lds_dwordx4 v[156:157], off
	v_lshl_add_u64 v[230:231], s[50:51], 0, v[128:129]
	s_mov_b32 m0, s77
	v_lshl_add_u64 v[232:233], s[26:27], 0, v[136:137]
	global_load_lds_dwordx4 v[230:231], off
	v_lshl_add_u64 v[230:231], s[50:51], 0, v[134:135]
	s_add_i32 m0, s77, 0x2000
	s_nop 0
	global_load_lds_dwordx4 v[230:231], off
	v_lshl_add_u64 v[230:231], s[26:27], 0, v[138:139]
	s_mov_b32 m0, s38
	s_nop 0
	global_load_lds_dwordx4 v[230:231], off
	s_mov_b32 m0, s39
	s_nop 0
	global_load_lds_dwordx4 v[232:233], off
	s_waitcnt vmcnt(8)
	s_waitcnt lgkmcnt(0)
	s_barrier
	s_setprio 3
	s_waitcnt lgkmcnt(0)
	v_mfma_f32_16x16x32_bf16 v[60:63], v[152:155], v[198:201], v[60:63]
	v_mfma_f32_16x16x32_bf16 v[52:55], v[174:177], v[198:201], v[52:55]
	v_mfma_f32_16x16x32_bf16 v[44:47], v[152:155], v[206:209], v[44:47]
	v_mfma_f32_16x16x32_bf16 v[36:39], v[174:177], v[206:209], v[36:39]
	v_mfma_f32_16x16x32_bf16 v[28:31], v[152:155], v[214:217], v[28:31]
	v_mfma_f32_16x16x32_bf16 v[20:23], v[174:177], v[214:217], v[20:23]
	v_mfma_f32_16x16x32_bf16 v[12:15], v[152:155], v[222:225], v[12:15]
	v_mfma_f32_16x16x32_bf16 v[4:7], v[174:177], v[222:225], v[4:7]
	v_mfma_f32_16x16x32_bf16 v[60:63], v[170:173], v[202:205], v[60:63]
	v_mfma_f32_16x16x32_bf16 v[52:55], v[178:181], v[202:205], v[52:55]
	v_mfma_f32_16x16x32_bf16 v[44:47], v[170:173], v[210:213], v[44:47]
	v_mfma_f32_16x16x32_bf16 v[36:39], v[178:181], v[210:213], v[36:39]
	v_mfma_f32_16x16x32_bf16 v[28:31], v[170:173], v[218:221], v[28:31]
	v_mfma_f32_16x16x32_bf16 v[20:23], v[178:181], v[218:221], v[20:23]
	v_mfma_f32_16x16x32_bf16 v[12:15], v[170:173], v[226:229], v[12:15]
	v_mfma_f32_16x16x32_bf16 v[4:7], v[178:181], v[226:229], v[4:7]
	s_setprio 0
	s_setprio 3
	v_mfma_f32_16x16x32_bf16 v[56:59], v[182:185], v[198:201], v[56:59]
	v_mfma_f32_16x16x32_bf16 v[48:51], v[190:193], v[198:201], v[48:51]
	v_mfma_f32_16x16x32_bf16 v[40:43], v[182:185], v[206:209], v[40:43]
	v_mfma_f32_16x16x32_bf16 v[32:35], v[190:193], v[206:209], v[32:35]
	v_mfma_f32_16x16x32_bf16 v[24:27], v[182:185], v[214:217], v[24:27]
	v_mfma_f32_16x16x32_bf16 v[16:19], v[190:193], v[214:217], v[16:19]
	v_mfma_f32_16x16x32_bf16 v[8:11], v[182:185], v[222:225], v[8:11]
	v_mfma_f32_16x16x32_bf16 v[0:3], v[190:193], v[222:225], v[0:3]
	v_mfma_f32_16x16x32_bf16 v[56:59], v[186:189], v[202:205], v[56:59]
	v_mfma_f32_16x16x32_bf16 v[48:51], v[194:197], v[202:205], v[48:51]
	v_mfma_f32_16x16x32_bf16 v[40:43], v[186:189], v[210:213], v[40:43]
	v_mfma_f32_16x16x32_bf16 v[32:35], v[194:197], v[210:213], v[32:35]
	v_mfma_f32_16x16x32_bf16 v[24:27], v[186:189], v[218:221], v[24:27]
	v_mfma_f32_16x16x32_bf16 v[16:19], v[194:197], v[218:221], v[16:19]
	v_mfma_f32_16x16x32_bf16 v[8:11], v[186:189], v[226:229], v[8:11]
	v_mfma_f32_16x16x32_bf16 v[0:3], v[194:197], v[226:229], v[0:3]
	s_setprio 0
	s_barrier
	s_add_i32 s50, 0, 0x18000
	v_add_u32_e32 v151, s50, v146
	s_add_i32 s51, 0, 0x1c000
	ds_read_b128 v[152:155], v151
	ds_read_b128 v[170:173], v151 offset:1024
	ds_read_b128 v[174:177], v151 offset:2048
	ds_read_b128 v[178:181], v151 offset:3072
	v_add_u32_e32 v151, s51, v146
	ds_read_b128 v[182:185], v151
	ds_read_b128 v[186:189], v151 offset:1024
	ds_read_b128 v[190:193], v151 offset:2048
	ds_read_b128 v[194:197], v151 offset:3072
	s_add_u32 s26, s26, 0x40000
	s_addc_u32 s27, s27, 0
	s_mov_b32 m0, s40
	v_lshl_add_u64 v[234:235], s[26:27], 0, v[138:139]
	ds_read_b128 v[198:201], v150 offset:32768
	ds_read_b128 v[202:205], v150 offset:33792
	ds_read_b128 v[206:209], v150 offset:34816
	ds_read_b128 v[210:213], v150 offset:35840
	ds_read_b128 v[214:217], v150 offset:36864
	ds_read_b128 v[218:221], v150 offset:37888
	ds_read_b128 v[222:225], v150 offset:38912
	ds_read_b128 v[226:229], v150 offset:39936
	global_load_lds_dwordx4 v[234:235], off
	v_lshl_add_u64 v[234:235], s[26:27], 0, v[136:137]
	s_mov_b32 m0, s41
	s_nop 0
	global_load_lds_dwordx4 v[234:235], off
	s_waitcnt vmcnt(8)
	s_waitcnt lgkmcnt(0)
	s_barrier
	s_setprio 3
	s_waitcnt lgkmcnt(0)
	v_mfma_f32_16x16x32_bf16 v[124:127], v[152:155], v[198:201], v[124:127]
	v_mfma_f32_16x16x32_bf16 v[116:119], v[174:177], v[198:201], v[116:119]
	v_mfma_f32_16x16x32_bf16 v[108:111], v[152:155], v[206:209], v[108:111]
	v_mfma_f32_16x16x32_bf16 v[100:103], v[174:177], v[206:209], v[100:103]
	v_mfma_f32_16x16x32_bf16 v[92:95], v[152:155], v[214:217], v[92:95]
	v_mfma_f32_16x16x32_bf16 v[84:87], v[174:177], v[214:217], v[84:87]
	v_mfma_f32_16x16x32_bf16 v[76:79], v[152:155], v[222:225], v[76:79]
	v_mfma_f32_16x16x32_bf16 v[68:71], v[174:177], v[222:225], v[68:71]
	v_mfma_f32_16x16x32_bf16 v[124:127], v[170:173], v[202:205], v[124:127]
	v_mfma_f32_16x16x32_bf16 v[116:119], v[178:181], v[202:205], v[116:119]
	v_mfma_f32_16x16x32_bf16 v[108:111], v[170:173], v[210:213], v[108:111]
	v_mfma_f32_16x16x32_bf16 v[100:103], v[178:181], v[210:213], v[100:103]
	v_mfma_f32_16x16x32_bf16 v[92:95], v[170:173], v[218:221], v[92:95]
	v_mfma_f32_16x16x32_bf16 v[84:87], v[178:181], v[218:221], v[84:87]
	v_mfma_f32_16x16x32_bf16 v[76:79], v[170:173], v[226:229], v[76:79]
	v_mfma_f32_16x16x32_bf16 v[68:71], v[178:181], v[226:229], v[68:71]
	s_setprio 0
	s_setprio 3
	v_mfma_f32_16x16x32_bf16 v[120:123], v[182:185], v[198:201], v[120:123]
	v_mfma_f32_16x16x32_bf16 v[112:115], v[190:193], v[198:201], v[112:115]
	v_mfma_f32_16x16x32_bf16 v[104:107], v[182:185], v[206:209], v[104:107]
	v_mfma_f32_16x16x32_bf16 v[96:99], v[190:193], v[206:209], v[96:99]
	v_mfma_f32_16x16x32_bf16 v[88:91], v[182:185], v[214:217], v[88:91]
	v_mfma_f32_16x16x32_bf16 v[80:83], v[190:193], v[214:217], v[80:83]
	v_mfma_f32_16x16x32_bf16 v[72:75], v[182:185], v[222:225], v[72:75]
	v_mfma_f32_16x16x32_bf16 v[64:67], v[190:193], v[222:225], v[64:67]
	v_mfma_f32_16x16x32_bf16 v[120:123], v[186:189], v[202:205], v[120:123]
	v_mfma_f32_16x16x32_bf16 v[112:115], v[194:197], v[202:205], v[112:115]
	v_mfma_f32_16x16x32_bf16 v[104:107], v[186:189], v[210:213], v[104:107]
	v_mfma_f32_16x16x32_bf16 v[96:99], v[194:197], v[210:213], v[96:99]
	v_mfma_f32_16x16x32_bf16 v[88:91], v[186:189], v[218:221], v[88:91]
	v_mfma_f32_16x16x32_bf16 v[80:83], v[194:197], v[218:221], v[80:83]
	v_mfma_f32_16x16x32_bf16 v[72:75], v[186:189], v[226:229], v[72:75]
	v_mfma_f32_16x16x32_bf16 v[64:67], v[194:197], v[226:229], v[64:67]
	s_setprio 0
	s_barrier
	s_add_i32 s26, s50, s37
	v_lshl_add_u64 v[144:145], v[144:145], 0, s[84:85]
	s_mov_b32 m0, s26
	ds_read_b128 v[198:201], v150 offset:49152
	ds_read_b128 v[202:205], v150 offset:50176
	ds_read_b128 v[206:209], v150 offset:51200
	ds_read_b128 v[210:213], v150 offset:52224
	ds_read_b128 v[214:217], v150 offset:53248
	ds_read_b128 v[218:221], v150 offset:54272
	ds_read_b128 v[222:225], v150 offset:55296
	ds_read_b128 v[226:229], v150 offset:56320
	global_load_lds_dwordx4 v[144:145], off
	s_add_i32 m0, s26, 0x2000
	s_add_u32 s24, s24, 0x40080
	v_lshl_add_u64 v[144:145], v[156:157], 0, s[84:85]
	s_addc_u32 s25, s25, 0
	s_add_i32 s26, s51, s37
	global_load_lds_dwordx4 v[144:145], off
	v_lshl_add_u64 v[144:145], s[24:25], 0, v[128:129]
	s_mov_b32 m0, s26
	s_nop 0
	global_load_lds_dwordx4 v[144:145], off
	v_lshl_add_u64 v[144:145], s[24:25], 0, v[134:135]
	s_add_i32 m0, s26, 0x2000
	s_nop 0
	global_load_lds_dwordx4 v[144:145], off
	v_lshl_add_u64 v[144:145], v[230:231], 0, s[84:85]
	s_mov_b32 m0, s42
	s_nop 0
	global_load_lds_dwordx4 v[144:145], off
	v_lshl_add_u64 v[144:145], v[232:233], 0, s[84:85]
	s_mov_b32 m0, s43
	s_nop 0
	global_load_lds_dwordx4 v[144:145], off
	s_waitcnt vmcnt(8)
	s_waitcnt lgkmcnt(0)
	s_barrier
	s_setprio 3
	s_waitcnt lgkmcnt(0)
	v_mfma_f32_16x16x32_bf16 v[60:63], v[152:155], v[198:201], v[60:63]
	v_mfma_f32_16x16x32_bf16 v[52:55], v[174:177], v[198:201], v[52:55]
	v_mfma_f32_16x16x32_bf16 v[44:47], v[152:155], v[206:209], v[44:47]
	v_mfma_f32_16x16x32_bf16 v[36:39], v[174:177], v[206:209], v[36:39]
	v_mfma_f32_16x16x32_bf16 v[28:31], v[152:155], v[214:217], v[28:31]
	v_mfma_f32_16x16x32_bf16 v[20:23], v[174:177], v[214:217], v[20:23]
	v_mfma_f32_16x16x32_bf16 v[12:15], v[152:155], v[222:225], v[12:15]
	v_mfma_f32_16x16x32_bf16 v[4:7], v[174:177], v[222:225], v[4:7]
	v_mfma_f32_16x16x32_bf16 v[60:63], v[170:173], v[202:205], v[60:63]
	v_mfma_f32_16x16x32_bf16 v[52:55], v[178:181], v[202:205], v[52:55]
	v_mfma_f32_16x16x32_bf16 v[44:47], v[170:173], v[210:213], v[44:47]
	v_mfma_f32_16x16x32_bf16 v[36:39], v[178:181], v[210:213], v[36:39]
	v_mfma_f32_16x16x32_bf16 v[28:31], v[170:173], v[218:221], v[28:31]
	v_mfma_f32_16x16x32_bf16 v[20:23], v[178:181], v[218:221], v[20:23]
	v_mfma_f32_16x16x32_bf16 v[12:15], v[170:173], v[226:229], v[12:15]
	v_mfma_f32_16x16x32_bf16 v[4:7], v[178:181], v[226:229], v[4:7]
	s_setprio 0
	s_setprio 3
	v_mfma_f32_16x16x32_bf16 v[56:59], v[182:185], v[198:201], v[56:59]
	v_mfma_f32_16x16x32_bf16 v[48:51], v[190:193], v[198:201], v[48:51]
	v_mfma_f32_16x16x32_bf16 v[40:43], v[182:185], v[206:209], v[40:43]
	v_mfma_f32_16x16x32_bf16 v[32:35], v[190:193], v[206:209], v[32:35]
	v_mfma_f32_16x16x32_bf16 v[24:27], v[182:185], v[214:217], v[24:27]
	v_mfma_f32_16x16x32_bf16 v[16:19], v[190:193], v[214:217], v[16:19]
	v_mfma_f32_16x16x32_bf16 v[8:11], v[182:185], v[222:225], v[8:11]
	v_mfma_f32_16x16x32_bf16 v[0:3], v[190:193], v[222:225], v[0:3]
	v_mfma_f32_16x16x32_bf16 v[56:59], v[186:189], v[202:205], v[56:59]
	v_mfma_f32_16x16x32_bf16 v[48:51], v[194:197], v[202:205], v[48:51]
	v_mfma_f32_16x16x32_bf16 v[40:43], v[186:189], v[210:213], v[40:43]
	v_mfma_f32_16x16x32_bf16 v[32:35], v[194:197], v[210:213], v[32:35]
	v_mfma_f32_16x16x32_bf16 v[24:27], v[186:189], v[218:221], v[24:27]
	v_mfma_f32_16x16x32_bf16 v[16:19], v[194:197], v[218:221], v[16:19]
	v_mfma_f32_16x16x32_bf16 v[8:11], v[186:189], v[226:229], v[8:11]
	v_mfma_f32_16x16x32_bf16 v[0:3], v[194:197], v[226:229], v[0:3]
	s_setprio 0
	s_barrier
	s_add_i32 s49, s49, 2
	s_add_u32 s20, s20, 0x100
	s_addc_u32 s21, s21, 0
	s_add_u32 s47, s47, 0x100
	s_addc_u32 s48, s48, 0
	s_cmp_gt_u32 s49, 13
	s_cbranch_scc0 .LBB0_355
	s_branch .Lit0_swi_skip
.Lit0_swi:
	s_add_u32 s24, s20, 0xfffc0080
	s_addc_u32 s25, s21, -1
	s_add_i32 s50, 0, 0x10000
	s_cmp_eq_u32 s49, 12
	s_cselect_b32 s27, s9, s25
	s_cselect_b32 s26, s19, s24
	v_add_u32_e32 v144, s50, v146
	s_cselect_b32 s25, s11, s48
	s_cselect_b32 s24, s46, s47
	s_add_i32 s77, 0, 0x14000
	ds_read_b128 v[152:155], v144
	ds_read_b128 v[170:173], v144 offset:1024
	ds_read_b128 v[174:177], v144 offset:2048
	ds_read_b128 v[178:181], v144 offset:3072
	v_add_u32_e32 v144, s77, v146
	ds_read_b128 v[182:185], v144
	ds_read_b128 v[186:189], v144 offset:1024
	ds_read_b128 v[190:193], v144 offset:2048
	ds_read_b128 v[194:197], v144 offset:3072
	v_lshl_add_u64 v[144:145], s[20:21], 0, v[140:141]
	s_add_i32 m0, s38, 0xc000
	ds_read_b128 v[198:201], v150
	ds_read_b128 v[202:205], v150 offset:1024
	ds_read_b128 v[206:209], v150 offset:2048
	ds_read_b128 v[210:213], v150 offset:3072
	ds_read_b128 v[214:217], v150 offset:4096
	ds_read_b128 v[218:221], v150 offset:5120
	ds_read_b128 v[222:225], v150 offset:6144
	ds_read_b128 v[226:229], v150 offset:7168
	global_load_lds_dwordx4 v[144:145], off
	v_lshl_add_u64 v[144:145], s[20:21], 0, v[142:143]
	s_add_i32 m0, s38, 0xe000
	s_nop 0
	global_load_lds_dwordx4 v[144:145], off
	s_waitcnt vmcnt(8)
	s_waitcnt lgkmcnt(0)
	s_barrier
	s_setprio 3
	s_waitcnt lgkmcnt(0)
	v_mfma_f32_16x16x32_bf16 v[124:127], v[152:155], v[198:201], 0
	v_mfma_f32_16x16x32_bf16 v[116:119], v[174:177], v[198:201], 0
	v_mfma_f32_16x16x32_bf16 v[108:111], v[152:155], v[206:209], 0
	v_mfma_f32_16x16x32_bf16 v[100:103], v[174:177], v[206:209], 0
	v_mfma_f32_16x16x32_bf16 v[92:95], v[152:155], v[214:217], 0
	v_mfma_f32_16x16x32_bf16 v[84:87], v[174:177], v[214:217], 0
	v_mfma_f32_16x16x32_bf16 v[76:79], v[152:155], v[222:225], 0
	v_mfma_f32_16x16x32_bf16 v[68:71], v[174:177], v[222:225], 0
	v_mfma_f32_16x16x32_bf16 v[124:127], v[170:173], v[202:205], v[124:127]
	v_mfma_f32_16x16x32_bf16 v[116:119], v[178:181], v[202:205], v[116:119]
	v_mfma_f32_16x16x32_bf16 v[108:111], v[170:173], v[210:213], v[108:111]
	v_mfma_f32_16x16x32_bf16 v[100:103], v[178:181], v[210:213], v[100:103]
	v_mfma_f32_16x16x32_bf16 v[92:95], v[170:173], v[218:221], v[92:95]
	v_mfma_f32_16x16x32_bf16 v[84:87], v[178:181], v[218:221], v[84:87]
	v_mfma_f32_16x16x32_bf16 v[76:79], v[170:173], v[226:229], v[76:79]
	v_mfma_f32_16x16x32_bf16 v[68:71], v[178:181], v[226:229], v[68:71]
	s_setprio 0
	s_setprio 3
	v_mfma_f32_16x16x32_bf16 v[120:123], v[182:185], v[198:201], 0
	v_mfma_f32_16x16x32_bf16 v[112:115], v[190:193], v[198:201], 0
	v_mfma_f32_16x16x32_bf16 v[104:107], v[182:185], v[206:209], 0
	v_mfma_f32_16x16x32_bf16 v[96:99], v[190:193], v[206:209], 0
	v_mfma_f32_16x16x32_bf16 v[88:91], v[182:185], v[214:217], 0
	v_mfma_f32_16x16x32_bf16 v[80:83], v[190:193], v[214:217], 0
	v_mfma_f32_16x16x32_bf16 v[72:75], v[182:185], v[222:225], 0
	v_mfma_f32_16x16x32_bf16 v[64:67], v[190:193], v[222:225], 0
	v_mfma_f32_16x16x32_bf16 v[120:123], v[186:189], v[202:205], v[120:123]
	v_mfma_f32_16x16x32_bf16 v[112:115], v[194:197], v[202:205], v[112:115]
	v_mfma_f32_16x16x32_bf16 v[104:107], v[186:189], v[210:213], v[104:107]
	v_mfma_f32_16x16x32_bf16 v[96:99], v[194:197], v[210:213], v[96:99]
	v_mfma_f32_16x16x32_bf16 v[88:91], v[186:189], v[218:221], v[88:91]
	v_mfma_f32_16x16x32_bf16 v[80:83], v[194:197], v[218:221], v[80:83]
	v_mfma_f32_16x16x32_bf16 v[72:75], v[186:189], v[226:229], v[72:75]
	v_mfma_f32_16x16x32_bf16 v[64:67], v[194:197], v[226:229], v[64:67]
	s_setprio 0
	s_barrier
	s_add_i32 s50, s50, s37
	v_lshl_add_u64 v[144:145], s[24:25], 0, v[128:129]
	s_mov_b32 m0, s50
	ds_read_b128 v[198:201], v150 offset:16384
	ds_read_b128 v[202:205], v150 offset:17408
	ds_read_b128 v[206:209], v150 offset:18432
	ds_read_b128 v[210:213], v150 offset:19456
	ds_read_b128 v[214:217], v150 offset:20480
	ds_read_b128 v[218:221], v150 offset:21504
	ds_read_b128 v[222:225], v150 offset:22528
	ds_read_b128 v[226:229], v150 offset:23552
	global_load_lds_dwordx4 v[144:145], off
	s_add_i32 m0, s50, 0x2000
	s_add_u32 s50, s24, 0x40000
	v_lshl_add_u64 v[156:157], s[24:25], 0, v[134:135]
	s_addc_u32 s51, s25, 0
	s_add_i32 s77, s77, s37
	global_load_lds_dwordx4 v[156:157], off
	v_lshl_add_u64 v[230:231], s[50:51], 0, v[128:129]
	s_mov_b32 m0, s77
	v_lshl_add_u64 v[232:233], s[26:27], 0, v[136:137]
	global_load_lds_dwordx4 v[230:231], off
	v_lshl_add_u64 v[230:231], s[50:51], 0, v[134:135]
	s_add_i32 m0, s77, 0x2000
	s_nop 0
	global_load_lds_dwordx4 v[230:231], off
	v_lshl_add_u64 v[230:231], s[26:27], 0, v[138:139]
	s_mov_b32 m0, s38
	s_nop 0
	global_load_lds_dwordx4 v[230:231], off
	s_mov_b32 m0, s39
	s_nop 0
	global_load_lds_dwordx4 v[232:233], off
	s_waitcnt vmcnt(8)
	s_waitcnt lgkmcnt(0)
	s_barrier
	s_setprio 3
	s_waitcnt lgkmcnt(0)
	v_mfma_f32_16x16x32_bf16 v[60:63], v[152:155], v[198:201], 0
	v_mfma_f32_16x16x32_bf16 v[52:55], v[174:177], v[198:201], 0
	v_mfma_f32_16x16x32_bf16 v[44:47], v[152:155], v[206:209], 0
	v_mfma_f32_16x16x32_bf16 v[36:39], v[174:177], v[206:209], 0
	v_mfma_f32_16x16x32_bf16 v[28:31], v[152:155], v[214:217], 0
	v_mfma_f32_16x16x32_bf16 v[20:23], v[174:177], v[214:217], 0
	v_mfma_f32_16x16x32_bf16 v[12:15], v[152:155], v[222:225], 0
	v_mfma_f32_16x16x32_bf16 v[4:7], v[174:177], v[222:225], 0
	v_mfma_f32_16x16x32_bf16 v[60:63], v[170:173], v[202:205], v[60:63]
	v_mfma_f32_16x16x32_bf16 v[52:55], v[178:181], v[202:205], v[52:55]
	v_mfma_f32_16x16x32_bf16 v[44:47], v[170:173], v[210:213], v[44:47]
	v_mfma_f32_16x16x32_bf16 v[36:39], v[178:181], v[210:213], v[36:39]
	v_mfma_f32_16x16x32_bf16 v[28:31], v[170:173], v[218:221], v[28:31]
	v_mfma_f32_16x16x32_bf16 v[20:23], v[178:181], v[218:221], v[20:23]
	v_mfma_f32_16x16x32_bf16 v[12:15], v[170:173], v[226:229], v[12:15]
	v_mfma_f32_16x16x32_bf16 v[4:7], v[178:181], v[226:229], v[4:7]
	s_setprio 0
	s_setprio 3
	v_mfma_f32_16x16x32_bf16 v[56:59], v[182:185], v[198:201], 0
	v_mfma_f32_16x16x32_bf16 v[48:51], v[190:193], v[198:201], 0
	v_mfma_f32_16x16x32_bf16 v[40:43], v[182:185], v[206:209], 0
	v_mfma_f32_16x16x32_bf16 v[32:35], v[190:193], v[206:209], 0
	v_mfma_f32_16x16x32_bf16 v[24:27], v[182:185], v[214:217], 0
	v_mfma_f32_16x16x32_bf16 v[16:19], v[190:193], v[214:217], 0
	v_mfma_f32_16x16x32_bf16 v[8:11], v[182:185], v[222:225], 0
	v_mfma_f32_16x16x32_bf16 v[0:3], v[190:193], v[222:225], 0
	v_mfma_f32_16x16x32_bf16 v[56:59], v[186:189], v[202:205], v[56:59]
	v_mfma_f32_16x16x32_bf16 v[48:51], v[194:197], v[202:205], v[48:51]
	v_mfma_f32_16x16x32_bf16 v[40:43], v[186:189], v[210:213], v[40:43]
	v_mfma_f32_16x16x32_bf16 v[32:35], v[194:197], v[210:213], v[32:35]
	v_mfma_f32_16x16x32_bf16 v[24:27], v[186:189], v[218:221], v[24:27]
	v_mfma_f32_16x16x32_bf16 v[16:19], v[194:197], v[218:221], v[16:19]
	v_mfma_f32_16x16x32_bf16 v[8:11], v[186:189], v[226:229], v[8:11]
	v_mfma_f32_16x16x32_bf16 v[0:3], v[194:197], v[226:229], v[0:3]
	s_setprio 0
	s_barrier
	s_add_i32 s50, 0, 0x18000
	v_add_u32_e32 v151, s50, v146
	s_add_i32 s51, 0, 0x1c000
	ds_read_b128 v[152:155], v151
	ds_read_b128 v[170:173], v151 offset:1024
	ds_read_b128 v[174:177], v151 offset:2048
	ds_read_b128 v[178:181], v151 offset:3072
	v_add_u32_e32 v151, s51, v146
	ds_read_b128 v[182:185], v151
	ds_read_b128 v[186:189], v151 offset:1024
	ds_read_b128 v[190:193], v151 offset:2048
	ds_read_b128 v[194:197], v151 offset:3072
	s_add_u32 s26, s26, 0x40000
	s_addc_u32 s27, s27, 0
	s_mov_b32 m0, s40
	v_lshl_add_u64 v[234:235], s[26:27], 0, v[138:139]
	ds_read_b128 v[198:201], v150 offset:32768
	ds_read_b128 v[202:205], v150 offset:33792
	ds_read_b128 v[206:209], v150 offset:34816
	ds_read_b128 v[210:213], v150 offset:35840
	ds_read_b128 v[214:217], v150 offset:36864
	ds_read_b128 v[218:221], v150 offset:37888
	ds_read_b128 v[222:225], v150 offset:38912
	ds_read_b128 v[226:229], v150 offset:39936
	global_load_lds_dwordx4 v[234:235], off
	v_lshl_add_u64 v[234:235], s[26:27], 0, v[136:137]
	s_mov_b32 m0, s41
	s_nop 0
	global_load_lds_dwordx4 v[234:235], off
	s_waitcnt vmcnt(8)
	s_waitcnt lgkmcnt(0)
	s_barrier
	s_setprio 3
	s_waitcnt lgkmcnt(0)
	v_mfma_f32_16x16x32_bf16 v[124:127], v[152:155], v[198:201], v[124:127]
	v_mfma_f32_16x16x32_bf16 v[116:119], v[174:177], v[198:201], v[116:119]
	v_mfma_f32_16x16x32_bf16 v[108:111], v[152:155], v[206:209], v[108:111]
	v_mfma_f32_16x16x32_bf16 v[100:103], v[174:177], v[206:209], v[100:103]
	v_mfma_f32_16x16x32_bf16 v[92:95], v[152:155], v[214:217], v[92:95]
	v_mfma_f32_16x16x32_bf16 v[84:87], v[174:177], v[214:217], v[84:87]
	v_mfma_f32_16x16x32_bf16 v[76:79], v[152:155], v[222:225], v[76:79]
	v_mfma_f32_16x16x32_bf16 v[68:71], v[174:177], v[222:225], v[68:71]
	v_mfma_f32_16x16x32_bf16 v[124:127], v[170:173], v[202:205], v[124:127]
	v_mfma_f32_16x16x32_bf16 v[116:119], v[178:181], v[202:205], v[116:119]
	v_mfma_f32_16x16x32_bf16 v[108:111], v[170:173], v[210:213], v[108:111]
	v_mfma_f32_16x16x32_bf16 v[100:103], v[178:181], v[210:213], v[100:103]
	v_mfma_f32_16x16x32_bf16 v[92:95], v[170:173], v[218:221], v[92:95]
	v_mfma_f32_16x16x32_bf16 v[84:87], v[178:181], v[218:221], v[84:87]
	v_mfma_f32_16x16x32_bf16 v[76:79], v[170:173], v[226:229], v[76:79]
	v_mfma_f32_16x16x32_bf16 v[68:71], v[178:181], v[226:229], v[68:71]
	s_setprio 0
	s_setprio 3
	v_mfma_f32_16x16x32_bf16 v[120:123], v[182:185], v[198:201], v[120:123]
	v_mfma_f32_16x16x32_bf16 v[112:115], v[190:193], v[198:201], v[112:115]
	v_mfma_f32_16x16x32_bf16 v[104:107], v[182:185], v[206:209], v[104:107]
	v_mfma_f32_16x16x32_bf16 v[96:99], v[190:193], v[206:209], v[96:99]
	v_mfma_f32_16x16x32_bf16 v[88:91], v[182:185], v[214:217], v[88:91]
	v_mfma_f32_16x16x32_bf16 v[80:83], v[190:193], v[214:217], v[80:83]
	v_mfma_f32_16x16x32_bf16 v[72:75], v[182:185], v[222:225], v[72:75]
	v_mfma_f32_16x16x32_bf16 v[64:67], v[190:193], v[222:225], v[64:67]
	v_mfma_f32_16x16x32_bf16 v[120:123], v[186:189], v[202:205], v[120:123]
	v_mfma_f32_16x16x32_bf16 v[112:115], v[194:197], v[202:205], v[112:115]
	v_mfma_f32_16x16x32_bf16 v[104:107], v[186:189], v[210:213], v[104:107]
	v_mfma_f32_16x16x32_bf16 v[96:99], v[194:197], v[210:213], v[96:99]
	v_mfma_f32_16x16x32_bf16 v[88:91], v[186:189], v[218:221], v[88:91]
	v_mfma_f32_16x16x32_bf16 v[80:83], v[194:197], v[218:221], v[80:83]
	v_mfma_f32_16x16x32_bf16 v[72:75], v[186:189], v[226:229], v[72:75]
	v_mfma_f32_16x16x32_bf16 v[64:67], v[194:197], v[226:229], v[64:67]
	s_setprio 0
	s_barrier
	s_add_i32 s26, s50, s37
	v_lshl_add_u64 v[144:145], v[144:145], 0, s[84:85]
	s_mov_b32 m0, s26
	ds_read_b128 v[198:201], v150 offset:49152
	ds_read_b128 v[202:205], v150 offset:50176
	ds_read_b128 v[206:209], v150 offset:51200
	ds_read_b128 v[210:213], v150 offset:52224
	ds_read_b128 v[214:217], v150 offset:53248
	ds_read_b128 v[218:221], v150 offset:54272
	ds_read_b128 v[222:225], v150 offset:55296
	ds_read_b128 v[226:229], v150 offset:56320
	global_load_lds_dwordx4 v[144:145], off
	s_add_i32 m0, s26, 0x2000
	s_add_u32 s24, s24, 0x40080
	v_lshl_add_u64 v[144:145], v[156:157], 0, s[84:85]
	s_addc_u32 s25, s25, 0
	s_add_i32 s26, s51, s37
	global_load_lds_dwordx4 v[144:145], off
	v_lshl_add_u64 v[144:145], s[24:25], 0, v[128:129]
	s_mov_b32 m0, s26
	s_nop 0
	global_load_lds_dwordx4 v[144:145], off
	v_lshl_add_u64 v[144:145], s[24:25], 0, v[134:135]
	s_add_i32 m0, s26, 0x2000
	s_nop 0
	global_load_lds_dwordx4 v[144:145], off
	v_lshl_add_u64 v[144:145], v[230:231], 0, s[84:85]
	s_mov_b32 m0, s42
	s_nop 0
	global_load_lds_dwordx4 v[144:145], off
	v_lshl_add_u64 v[144:145], v[232:233], 0, s[84:85]
	s_mov_b32 m0, s43
	s_nop 0
	global_load_lds_dwordx4 v[144:145], off
	s_waitcnt vmcnt(8)
	s_waitcnt lgkmcnt(0)
	s_barrier
	s_setprio 3
	s_waitcnt lgkmcnt(0)
	v_mfma_f32_16x16x32_bf16 v[60:63], v[152:155], v[198:201], v[60:63]
	v_mfma_f32_16x16x32_bf16 v[52:55], v[174:177], v[198:201], v[52:55]
	v_mfma_f32_16x16x32_bf16 v[44:47], v[152:155], v[206:209], v[44:47]
	v_mfma_f32_16x16x32_bf16 v[36:39], v[174:177], v[206:209], v[36:39]
	v_mfma_f32_16x16x32_bf16 v[28:31], v[152:155], v[214:217], v[28:31]
	v_mfma_f32_16x16x32_bf16 v[20:23], v[174:177], v[214:217], v[20:23]
	v_mfma_f32_16x16x32_bf16 v[12:15], v[152:155], v[222:225], v[12:15]
	v_mfma_f32_16x16x32_bf16 v[4:7], v[174:177], v[222:225], v[4:7]
	v_mfma_f32_16x16x32_bf16 v[60:63], v[170:173], v[202:205], v[60:63]
	v_mfma_f32_16x16x32_bf16 v[52:55], v[178:181], v[202:205], v[52:55]
	v_mfma_f32_16x16x32_bf16 v[44:47], v[170:173], v[210:213], v[44:47]
	v_mfma_f32_16x16x32_bf16 v[36:39], v[178:181], v[210:213], v[36:39]
	v_mfma_f32_16x16x32_bf16 v[28:31], v[170:173], v[218:221], v[28:31]
	v_mfma_f32_16x16x32_bf16 v[20:23], v[178:181], v[218:221], v[20:23]
	v_mfma_f32_16x16x32_bf16 v[12:15], v[170:173], v[226:229], v[12:15]
	v_mfma_f32_16x16x32_bf16 v[4:7], v[178:181], v[226:229], v[4:7]
	s_setprio 0
	s_setprio 3
	v_mfma_f32_16x16x32_bf16 v[56:59], v[182:185], v[198:201], v[56:59]
	v_mfma_f32_16x16x32_bf16 v[48:51], v[190:193], v[198:201], v[48:51]
	v_mfma_f32_16x16x32_bf16 v[40:43], v[182:185], v[206:209], v[40:43]
	v_mfma_f32_16x16x32_bf16 v[32:35], v[190:193], v[206:209], v[32:35]
	v_mfma_f32_16x16x32_bf16 v[24:27], v[182:185], v[214:217], v[24:27]
	v_mfma_f32_16x16x32_bf16 v[16:19], v[190:193], v[214:217], v[16:19]
	v_mfma_f32_16x16x32_bf16 v[8:11], v[182:185], v[222:225], v[8:11]
	v_mfma_f32_16x16x32_bf16 v[0:3], v[190:193], v[222:225], v[0:3]
	v_mfma_f32_16x16x32_bf16 v[56:59], v[186:189], v[202:205], v[56:59]
	v_mfma_f32_16x16x32_bf16 v[48:51], v[194:197], v[202:205], v[48:51]
	v_mfma_f32_16x16x32_bf16 v[40:43], v[186:189], v[210:213], v[40:43]
	v_mfma_f32_16x16x32_bf16 v[32:35], v[194:197], v[210:213], v[32:35]
	v_mfma_f32_16x16x32_bf16 v[24:27], v[186:189], v[218:221], v[24:27]
	v_mfma_f32_16x16x32_bf16 v[16:19], v[194:197], v[218:221], v[16:19]
	v_mfma_f32_16x16x32_bf16 v[8:11], v[186:189], v[226:229], v[8:11]
	v_mfma_f32_16x16x32_bf16 v[0:3], v[194:197], v[226:229], v[0:3]
	s_setprio 0
	s_barrier
	s_add_i32 s49, s49, 2
	s_add_u32 s20, s20, 0x100
	s_addc_u32 s21, s21, 0
	s_add_u32 s47, s47, 0x100
	s_addc_u32 s48, s48, 0
	s_cmp_gt_u32 s49, 13
	s_branch .LBB0_355
